# attention Q fragments kept in VGPRs instead of LDS re-reads; retention state-update transposed LDS reads remapped to conflict-free rows
# speedup vs baseline: 1.0033x; 1.0033x over previous
; #define LAS __attribute__((address_space(3)))
;     DI void loadk(int t, bf16x8 (&kn)[4]) const { attn_load_k(P, tokbase, EIN, kcol, 1, 0, SEQ, (rsA + t) * 64 + c0, lane, kn); }
;     DI void loadv(int t, bf16x8 (&vn)[4]) const { attn_load_v(P, tokbase, EIN, vcol, 1, 0, SEQ, (rsA + t) * 64 + c0, lane, vn); }
;     DI void loadk(int T, bf16x8 (&kn)[4]) const { const int sh = sh_of(T); attn_load_k(P, tokbase, EIN, kcol, 1 << sh, r & ((1 << sh) - 1), SEQ >> sh, m0_of(T), lane, kn); }
;     DI void loadv(int T, bf16x8 (&vn)[4]) const { const int sh = sh_of(T); attn_load_v(P, tokbase, EIN, vcol, 1 << sh, r & ((1 << sh) - 1), SEQ >> sh, m0_of(T), lane, vn); }
; template <class Desc>
; DI void attn_loop(const Desc& d, int ntiles, const bf16x8 (&qf)[4], LAS unsigned char* LV, int lane, bf16_t* orow) {
;     LAS unsigned char* LQ = LV + ATT_V_BYTES;
;     asm volatile("" ::: "memory");
; #pragma unroll
;     for (int c = 0; c < 4; ++c) lds_w128(LQ, c * 1024 + lane * 16, qf[c]);
;     asm volatile("" ::: "memory");
;     f32x16 O0, O1;
; #pragma unroll
;     for (int i = 0; i < 16; ++i) { O0[i] = 0.f; O1[i] = 0.f; }
;     float m_run = -1e30f, l_run = 0.f;
;     bf16x8 kA[4], kB[4], vN[4];
;     const int tl = ntiles - 1;
;     d.loadk(0, kA); d.loadv(0, vN); d.loadk(1 < tl ? 1 : tl, kB);
; DI void dil_item(int item, const bf16_t* P, bf16_t* Oo, LAS unsigned char* LV, int lane) {
;     const int mblk = item & 7, r = (item >> 3) & 15, head = (item >> 7) & 7, seq = item >> 10;
;     const size_t tokbase = (size_t)seq * SEQ;
;     const int h = lane >> 5, tq = 16 * (32 * mblk + (lane & 31)) + r;
;     bf16x8 qf[4];
;     { const bf16_t* qp = P + (tokbase + tq) * EIN + 1536 + head * 64 + 8 * h;
; #pragma unroll
;       for (int c = 0; c < 4; ++c) qf[c] = *(const bf16x8*)(qp + 16 * c); }
;     const DilDesc d{P, tokbase, lane, 2048 + head * 64, 2560 + head * 64, mblk, r, tq};
;     attn_loop(d, 33, qf, LV, lane, Oo + (tokbase + tq) * D + 512 + head * 64);
; }
.LBB0_311:
	v_cmp_le_i32_e32 vcc, s84, v113
	v_lshrrev_b32_e32 v5, 1, v113
	v_add_u32_e32 v158, v115, v119
	v_lshlrev_b32_e32 v0, 1, v112
	s_and_saveexec_b64 s[38:39], vcc
	s_xor_b64 s[96:97], exec, s[38:39]
	s_cbranch_execz .LBB0_339
	v_subrev_u32_e32 v2, s84, v113
	v_bfe_u32 v137, v113, 3, 4
	v_lshrrev_b32_e32 v2, 10, v2
	v_mov_b32_e32 v3, v1
	v_lshlrev_b64 v[46:47], 12, v[2:3]
	v_or_b32_e32 v142, v137, v152
	v_or_b32_e32 v134, v46, v142
	v_mov_b64_e32 v[18:19], s[86:87]
	v_mad_u64_u32 v[2:3], s[38:39], v134, s90, v[18:19]
	v_and_b32_e32 v136, 0x1c0, v5
	v_mad_u32_u24 v3, v47, s90, v3
	v_lshlrev_b32_e32 v20, 1, v136
	v_mov_b32_e32 v21, v1
	v_lshl_add_u64 v[2:3], v[2:3], 0, v[20:21]
	v_lshl_add_u64 v[14:15], v[2:3], 0, v[0:1]
	global_load_dwordx4 v[2:5], v[14:15], off offset:3072
	global_load_dwordx4 v[6:9], v[14:15], off offset:3104
	global_load_dwordx4 v[10:13], v[14:15], off offset:3136
	s_nop 0
	global_load_dwordx4 v[14:17], v[14:15], off offset:3168
	v_or_b32_e32 v22, v46, v118
	v_mov_b32_e32 v133, v1
	v_or_b32_e32 v48, 0x1000, v20
	v_lshl_add_u64 v[20:21], s[86:87], 0, v[20:21]
	v_mad_u64_u32 v[22:23], s[38:39], v22, s90, v[18:19]
	v_lshl_add_u64 v[20:21], v[20:21], 0, v[132:133]
	v_or_b32_e32 v28, v46, v128
	s_mov_b64 s[38:39], 0x1400
	v_mov_b32_e32 v49, v1
	v_or_b32_e32 v24, v46, v120
	v_or_b32_e32 v25, v46, v122
	v_or_b32_e32 v26, v46, v124
	v_or_b32_e32 v27, v46, v126
	v_lshl_add_u64 v[138:139], v[20:21], 0, s[38:39]
	v_mad_u64_u32 v[18:19], s[38:39], v28, s90, v[18:19]
	v_mad_u32_u24 v23, v47, s90, v23
	v_mad_u64_u32 v[30:31], s[38:39], v24, s90, v[138:139]
	v_mad_u64_u32 v[32:33], s[38:39], v25, s90, v[138:139]
	v_mad_u64_u32 v[38:39], s[38:39], v26, s90, v[138:139]
	v_mad_u64_u32 v[40:41], s[38:39], v27, s90, v[138:139]
	v_mad_u32_u24 v19, v47, s90, v19
	v_lshl_add_u64 v[20:21], v[22:23], 0, v[48:49]
	v_mad_u32_u24 v31, v47, s90, v31
	v_mad_u32_u24 v33, v47, s90, v33
	v_mad_u32_u24 v39, v47, s90, v39
	v_mad_u32_u24 v41, v47, s90, v41
	v_lshl_add_u64 v[18:19], v[18:19], 0, v[48:49]
	v_lshl_add_u64 v[20:21], v[20:21], 0, v[0:1]
	v_lshl_add_u64 v[50:51], v[18:19], 0, v[0:1]
	v_lshl_add_u64 v[140:141], v[116:117], 0, v[48:49]
	v_mov_b32_e32 v0, v1
	v_mov_b32_e32 v135, v47
	s_mov_b32 s44, 0
	v_mov_b32_e32 v160, 0
	v_mov_b32_e32 v133, 0xf149f2ca
	s_waitcnt vmcnt(3)
	v_mov_b64_e32 v[236:237], v[2:3]
	v_mov_b64_e32 v[238:239], v[4:5]
	s_waitcnt vmcnt(2)
	v_mov_b64_e32 v[240:241], v[6:7]
	v_mov_b64_e32 v[242:243], v[8:9]
	s_waitcnt vmcnt(1)
	v_mov_b64_e32 v[244:245], v[10:11]
	v_mov_b64_e32 v[246:247], v[12:13]
	s_waitcnt vmcnt(0)
	v_mov_b64_e32 v[248:249], v[14:15]
	v_mov_b64_e32 v[250:251], v[16:17]
	global_load_dwordx4 v[34:37], v[20:21], off
	global_load_dwordx4 v[26:29], v[20:21], off offset:32
	global_load_dwordx4 v[22:25], v[20:21], off offset:64
	s_nop 0
	global_load_dwordx4 v[18:21], v[20:21], off offset:96
	s_nop 0
	global_load_dwordx4 v[96:99], v[30:31], off
	global_load_dwordx4 v[100:103], v[32:33], off
	global_load_dwordx4 v[104:107], v[38:39], off
	global_load_dwordx4 v[108:111], v[40:41], off
	global_load_dwordx4 v[80:83], v[50:51], off
	global_load_dwordx4 v[42:45], v[50:51], off offset:32
	s_nop 0
	global_load_dwordx4 v[38:41], v[50:51], off offset:64
	global_load_dwordx4 v[30:33], v[50:51], off offset:96
	v_mov_b32_e32 v14, v1
	v_mov_b32_e32 v15, v1
	v_mov_b32_e32 v2, v1
	v_mov_b32_e32 v3, v1
	v_mov_b32_e32 v4, v1
	v_mov_b32_e32 v5, v1
	v_mov_b32_e32 v6, v1
	v_mov_b32_e32 v7, v1
	v_mov_b32_e32 v8, v1
	v_mov_b32_e32 v9, v1
	v_mov_b32_e32 v10, v1
	v_mov_b32_e32 v11, v1
	v_mov_b32_e32 v12, v1
	v_mov_b32_e32 v13, v1
	v_mov_b64_e32 v[62:63], v[14:15]
	v_mov_b64_e32 v[78:79], v[14:15]
	v_mov_b64_e32 v[60:61], v[12:13]
	v_mov_b64_e32 v[58:59], v[10:11]
	v_mov_b64_e32 v[56:57], v[8:9]
	v_mov_b64_e32 v[54:55], v[6:7]
	v_mov_b64_e32 v[52:53], v[4:5]
	v_mov_b64_e32 v[50:51], v[2:3]
	v_mov_b64_e32 v[48:49], v[0:1]
	v_mov_b64_e32 v[76:77], v[12:13]
	v_mov_b64_e32 v[74:75], v[10:11]
	v_mov_b64_e32 v[72:73], v[8:9]
	v_mov_b64_e32 v[70:71], v[6:7]
	v_mov_b64_e32 v[68:69], v[4:5]
	v_mov_b64_e32 v[66:67], v[2:3]
	v_mov_b64_e32 v[64:65], v[0:1]
	s_branch .LBB0_315

; #define LAS __attribute__((address_space(3)))
; DI float fexp2(float x) { return __builtin_amdgcn_exp2f(x); }
; DI float shx(float v, int o) { int l = (int)__builtin_amdgcn_mbcnt_hi(~0u, __builtin_amdgcn_mbcnt_lo(~0u, 0u)); asm volatile("" : "+v"(l)); return __int_as_float(__builtin_amdgcn_ds_bpermute((l ^ o) << 2, __float_as_int(v))); }
; DI f32x16 mfma32(bf16x8 a, bf16x8 b, f32x16 c) { return __builtin_amdgcn_mfma_f32_32x32x16_bf16(a, b, c, 0, 0, 0); }
;     DI void loadk(int t, bf16x8 (&kn)[4]) const { attn_load_k(P, tokbase, EIN, kcol, 1, 0, SEQ, (rsA + t) * 64 + c0, lane, kn); }
;     DI void loadv(int t, bf16x8 (&vn)[4]) const { attn_load_v(P, tokbase, EIN, vcol, 1, 0, SEQ, (rsA + t) * 64 + c0, lane, vn); }
;     DI void rest(int t, const f32x16& S, LAS unsigned char* LV, int ln, f32x16& O0, f32x16& O1, float& m_run, float& l_run) const { attn_rest(S, LV, ln, O0, O1, m_run, l_run, mask(t)); }
; DI f32x16 attn_scores(LAS unsigned char* LQ, int lane, const bf16x8 (&kf)[4]) {
;     f32x16 S;
; #pragma unroll
;     for (int i = 0; i < 16; ++i) S[i] = 0.f;
; #pragma unroll
;     for (int c = 0; c < 4; ++c) S = mfma32(kf[c], lds_r128(LQ, c * 1024 + lane * 16), S);
;     return S;
; }
; template <class MaskF>
; DI void attn_rest(const f32x16& S, LAS unsigned char* LV, int lane, f32x16& O0, f32x16& O1, float& m_run, float& l_run, const MaskF& maskf) {
;     const int h = lane >> 5;
;     float sv[16]; float mx = -1e30f;
; #pragma unroll
;     for (int r = 0; r < 16; ++r) { sv[r] = maskf((r & 3) + 8 * (r >> 2), S[r]); mx = fmaxf(mx, sv[r]); }
;     mx = fmaxf(mx, shx(mx, 32));
;     if (__builtin_amdgcn_ballot_w64(mx > m_run) != 0ull) {
;         const float mn = fmaxf(m_run, mx);
;         const float alpha = fexp2(m_run - mn);
;         m_run = mn; l_run *= alpha;
; #pragma unroll
;         for (int i = 0; i < 16; ++i) { O0[i] *= alpha; O1[i] *= alpha; }
;     }
; template <class Desc>
; DI void attn_loop(const Desc& d, int ntiles, const bf16x8 (&qf)[4], LAS unsigned char* LV, int lane, bf16_t* orow) {
;     ...
;     for (int t = 0; t + 1 < ntiles; t += 2) {
;         const f32x16 Sa = attn_scores(LQ, lane, kA);
;         d.loadk(t + 2 < tl ? t + 2 : tl, kA);
;         attn_store_v(LV, lane, vN);
;         d.loadv(t + 1, vN);
;         d.rest(t, Sa, LV, lane, O0, O1, m_run, l_run);
.LBB0_315:
	s_cmp_lt_u32 s44, 26
	s_cselect_b32 s38, 2, 4
	s_cselect_b32 s39, s48, 0xffffffe4
	s_cmp_lt_u32 s44, 18
	s_waitcnt vmcnt(11) lgkmcnt(0)
	v_mfma_f32_32x32x16_bf16 v[2:17], v[34:37], v[236:239], 0
	s_cselect_b32 s46, 0, s38
	s_cselect_b32 s38, 0, s39
	s_add_i32 s38, s38, s44
	v_lshrrev_b32_e32 v0, s46, v151
	s_lshl_b32 s38, s38, 5
	v_add3_u32 v0, s38, 64, v0
	s_waitcnt vmcnt(10) lgkmcnt(0)
	v_mfma_f32_32x32x16_bf16 v[2:17], v[26:29], v[240:243], v[2:17]
	s_lshr_b32 s47, 0x1000, s46
	v_subrev_u32_e32 v163, 64, v0
	v_add_u32_e32 v0, v163, v121
	s_add_i32 s47, s47, -1
	v_cmp_lt_i32_e32 vcc, -1, v0
	v_bfe_u32 v162, v137, 0, s46
	s_waitcnt vmcnt(9) lgkmcnt(0)
	v_mfma_f32_32x32x16_bf16 v[2:17], v[22:25], v[244:247], v[2:17]
	s_cmp_lt_u32 s44, 28
	v_add_u32_e32 v143, v125, v127
	s_waitcnt vmcnt(8) lgkmcnt(0)
	v_mfma_f32_32x32x16_bf16 v[2:17], v[18:21], v[248:251], v[2:17]
	v_min_u32_e32 v18, s47, v0
	v_cndmask_b32_e32 v0, 0, v18, vcc
	v_lshl_add_u32 v0, v0, s46, v162
	v_lshl_add_u64 v[18:19], v[46:47], 0, v[0:1]
	v_mad_u64_u32 v[20:21], s[38:39], v18, s90, v[140:141]
	s_cselect_b32 s38, 2, 4
	s_cselect_b32 s39, s48, 0xffffffe4
	s_cmp_lt_u32 s44, 20
	s_cselect_b32 s49, 0, s38
	s_cselect_b32 s38, 0, s39
	v_mad_u32_u24 v21, v19, s90, v21
	s_add_i32 s38, s38, s44
	global_load_dwordx4 v[34:37], v[20:21], off
	global_load_dwordx4 v[26:29], v[20:21], off offset:32
	global_load_dwordx4 v[22:25], v[20:21], off offset:64
	s_nop 0
	global_load_dwordx4 v[18:21], v[20:21], off offset:96
	s_waitcnt vmcnt(7)
	ds_write_b128 v143, v[96:99] offset:16384
	s_waitcnt vmcnt(6)
	ds_write_b128 v143, v[100:103] offset:17920
	s_waitcnt vmcnt(5)
	ds_write_b128 v143, v[104:107] offset:19456
	s_waitcnt vmcnt(4)
	ds_write_b128 v143, v[108:111] offset:20992
	v_lshrrev_b32_e32 v100, s49, v151
	s_lshl_b32 s52, s38, 5
	v_add3_u32 v159, s52, 32, v100
	s_lshr_b32 s45, 0x1000, s49
	v_subrev_u32_e32 v161, 64, v159
	v_or_b32_e32 v97, v161, v123
	s_add_i32 s53, s45, -1
	v_cmp_gt_i32_e64 s[38:39], 0, v161
	v_min_u32_e32 v0, s53, v97
	v_bfe_u32 v96, v137, 0, s49
	v_cndmask_b32_e64 v0, v0, 0, s[38:39]
	v_lshl_add_u32 v0, v0, s49, v96
	v_lshl_add_u64 v[84:85], v[46:47], 0, v[0:1]
	v_add_u32_e32 v0, 8, v97
	v_min_u32_e32 v88, s53, v0
	v_cmp_lt_i32_e32 vcc, -1, v0
	v_mad_u64_u32 v[86:87], s[40:41], v84, s90, v[138:139]
	s_nop 0
	v_cndmask_b32_e32 v0, 0, v88, vcc
	v_lshl_add_u32 v0, v0, s49, v96
	v_lshl_add_u64 v[88:89], v[46:47], 0, v[0:1]
	v_add_u32_e32 v0, 16, v97
	v_min_u32_e32 v92, s53, v0
	v_cmp_lt_i32_e32 vcc, -1, v0
	v_mad_u64_u32 v[90:91], s[40:41], v88, s90, v[138:139]
	s_nop 0
	v_cndmask_b32_e32 v0, 0, v92, vcc
	v_lshl_add_u32 v0, v0, s49, v96
	v_lshl_add_u64 v[92:93], v[46:47], 0, v[0:1]
	v_add_u32_e32 v0, 24, v97
	v_min_u32_e32 v97, s53, v0
	v_cmp_lt_i32_e32 vcc, -1, v0
	v_mad_u64_u32 v[94:95], s[40:41], v92, s90, v[138:139]
	s_nop 0
	v_cndmask_b32_e32 v0, 0, v97, vcc
	v_lshl_add_u32 v0, v0, s49, v96
	v_lshl_add_u64 v[96:97], v[46:47], 0, v[0:1]
	v_mad_u64_u32 v[98:99], s[40:41], v96, s90, v[138:139]
	v_mad_u32_u24 v87, v85, s90, v87
	v_mad_u32_u24 v91, v89, s90, v91
	v_mad_u32_u24 v95, v93, s90, v95
	v_mad_u32_u24 v99, v97, s90, v99
	global_load_dwordx4 v[84:87], v[86:87], off
	v_add_u32_e32 v0, s52, v100
	global_load_dwordx4 v[88:91], v[90:91], off
	v_subrev_u32_e32 v100, 64, v0
	global_load_dwordx4 v[92:95], v[94:95], off
	v_subrev_u32_e32 v101, 32, v0
	global_load_dwordx4 v[96:99], v[98:99], off
	v_cmp_lt_i32_e32 vcc, -1, v100
	v_cmp_ge_i32_e64 s[40:41], s45, v101
	s_and_b64 s[40:41], vcc, s[40:41]
	v_lshrrev_b32_e32 v164, s49, v142
	s_and_saveexec_b64 s[52:53], s[40:41]
	s_xor_b64 s[40:41], exec, s[52:53]
	s_cbranch_execz .LBB0_319
	v_sub_u32_e32 v0, v0, v164
	v_add_u32_e32 v107, v0, v114
	v_cmp_gt_u32_e32 vcc, s82, v107
	v_add_u32_e32 v0, 1, v107
	s_nop 0
	v_cndmask_b32_e32 v106, v229, v2, vcc
	v_cmp_gt_u32_e32 vcc, s82, v0
	v_add_u32_e32 v2, 2, v107
	s_nop 0
	v_cndmask_b32_e32 v105, v229, v3, vcc
	v_cmp_gt_u32_e32 vcc, s82, v2
	v_add_u32_e32 v2, 3, v107
	v_max3_f32 v0, v106, s83, v105
	v_cndmask_b32_e32 v104, v229, v4, vcc
	v_cmp_gt_u32_e32 vcc, s82, v2
	v_add_u32_e32 v2, 8, v107
	v_add_u32_e32 v3, 25, v107
	v_cndmask_b32_e32 v103, v229, v5, vcc
	v_cmp_gt_u32_e32 vcc, s82, v2
	v_add_u32_e32 v2, 9, v107
	v_max3_f32 v0, v0, v104, v103
	v_cndmask_b32_e32 v102, v229, v6, vcc
	v_cmp_gt_u32_e32 vcc, s82, v2
	v_add_u32_e32 v2, 10, v107
	v_add_u32_e32 v5, 27, v107
	v_cndmask_b32_e32 v101, v229, v7, vcc
	v_cmp_gt_u32_e32 vcc, s82, v2
	v_add_u32_e32 v2, 11, v107
	v_max3_f32 v0, v0, v102, v101
	v_cndmask_b32_e32 v100, v229, v8, vcc
	v_cmp_gt_u32_e32 vcc, s82, v2
	v_add_u32_e32 v2, 16, v107
	s_nop 0
	v_cndmask_b32_e32 v9, v229, v9, vcc
	v_cmp_gt_u32_e32 vcc, s82, v2
	v_add_u32_e32 v2, 17, v107
	v_max3_f32 v0, v0, v100, v9
	v_cndmask_b32_e32 v8, v229, v10, vcc
	v_cmp_gt_u32_e32 vcc, s82, v2
	s_nop 1
	v_cndmask_b32_e32 v7, v229, v11, vcc
	v_max3_f32 v2, v0, v8, v7
	v_add_u32_e32 v0, 18, v107
	v_cmp_gt_u32_e32 vcc, s82, v0
	v_add_u32_e32 v0, 19, v107
	v_mov_b32_e32 v11, v205
	v_cndmask_b32_e32 v6, v229, v12, vcc
	v_cmp_gt_u32_e32 vcc, s82, v0
	s_nop 0
	v_lshlrev_b32_e32 v11, 2, v11
	v_cndmask_b32_e32 v0, v229, v13, vcc
	v_max3_f32 v4, v2, v6, v0
	v_add_u32_e32 v2, 24, v107
	v_cmp_gt_u32_e32 vcc, s82, v2
	v_xor_b32_e32 v11, 0x80, v11
	s_nop 0
	v_cndmask_b32_e32 v2, v229, v14, vcc
	v_cmp_gt_u32_e32 vcc, s82, v3
	s_nop 1
	v_cndmask_b32_e32 v3, v229, v15, vcc
	v_max3_f32 v10, v4, v2, v3
	v_add_u32_e32 v4, 26, v107
	v_cmp_gt_u32_e32 vcc, s82, v4
	s_nop 1
	v_cndmask_b32_e32 v4, v229, v16, vcc
	v_cmp_gt_u32_e32 vcc, s82, v5
	s_nop 1
	v_cndmask_b32_e32 v5, v229, v17, vcc
	v_max3_f32 v10, v10, v4, v5
	ds_bpermute_b32 v11, v11, v10
	s_waitcnt lgkmcnt(0)
	v_max_f32_e32 v11, v11, v11
	v_max_f32_e32 v10, v10, v11
	v_cmp_gt_f32_e32 vcc, v10, v133
	s_cbranch_vccz .LBB0_318
	v_max_f32_e32 v10, v10, v10
	v_max_f32_e32 v11, v133, v133
	v_max_f32_e32 v11, v11, v10
	v_sub_f32_e32 v10, v133, v11
	v_exp_f32_e32 v10, v10
	v_mov_b32_e32 v133, v11
	v_mul_f32_e32 v160, v160, v10
	v_pk_mul_f32 v[62:63], v[62:63], v[10:11] op_sel_hi:[1,0]
	v_pk_mul_f32 v[60:61], v[60:61], v[10:11] op_sel_hi:[1,0]
	v_pk_mul_f32 v[58:59], v[58:59], v[10:11] op_sel_hi:[1,0]
	v_pk_mul_f32 v[56:57], v[56:57], v[10:11] op_sel_hi:[1,0]
	v_pk_mul_f32 v[54:55], v[54:55], v[10:11] op_sel_hi:[1,0]
	v_pk_mul_f32 v[52:53], v[52:53], v[10:11] op_sel_hi:[1,0]
	v_pk_mul_f32 v[50:51], v[50:51], v[10:11] op_sel_hi:[1,0]
	v_pk_mul_f32 v[48:49], v[48:49], v[10:11] op_sel_hi:[1,0]
	v_pk_mul_f32 v[78:79], v[78:79], v[10:11] op_sel_hi:[1,0]
	v_pk_mul_f32 v[76:77], v[76:77], v[10:11] op_sel_hi:[1,0]
	v_pk_mul_f32 v[74:75], v[74:75], v[10:11] op_sel_hi:[1,0]
	v_pk_mul_f32 v[72:73], v[72:73], v[10:11] op_sel_hi:[1,0]
	v_pk_mul_f32 v[70:71], v[70:71], v[10:11] op_sel_hi:[1,0]
	v_pk_mul_f32 v[68:69], v[68:69], v[10:11] op_sel_hi:[1,0]
	v_pk_mul_f32 v[66:67], v[66:67], v[10:11] op_sel_hi:[1,0]
	v_pk_mul_f32 v[64:65], v[64:65], v[10:11] op_sel_hi:[1,0]

; #define LAS __attribute__((address_space(3)))
; DI float fexp2(float x) { return __builtin_amdgcn_exp2f(x); }
; DI float shx(float v, int o) { int l = (int)__builtin_amdgcn_mbcnt_hi(~0u, __builtin_amdgcn_mbcnt_lo(~0u, 0u)); asm volatile("" : "+v"(l)); return __int_as_float(__builtin_amdgcn_ds_bpermute((l ^ o) << 2, __float_as_int(v))); }
; DI f32x16 mfma32(bf16x8 a, bf16x8 b, f32x16 c) { return __builtin_amdgcn_mfma_f32_32x32x16_bf16(a, b, c, 0, 0, 0); }
;     DI void loadk(int t, bf16x8 (&kn)[4]) const { attn_load_k(P, tokbase, EIN, kcol, 1, 0, SEQ, (rsA + t) * 64 + c0, lane, kn); }
;     DI void loadv(int t, bf16x8 (&vn)[4]) const { attn_load_v(P, tokbase, EIN, vcol, 1, 0, SEQ, (rsA + t) * 64 + c0, lane, vn); }
;     DI void rest(int t, const f32x16& S, LAS unsigned char* LV, int ln, f32x16& O0, f32x16& O1, float& m_run, float& l_run) const { attn_rest(S, LV, ln, O0, O1, m_run, l_run, mask(t)); }
; DI f32x16 attn_scores(LAS unsigned char* LQ, int lane, const bf16x8 (&kf)[4]) {
;     f32x16 S;
; #pragma unroll
;     for (int i = 0; i < 16; ++i) S[i] = 0.f;
; #pragma unroll
;     for (int c = 0; c < 4; ++c) S = mfma32(kf[c], lds_r128(LQ, c * 1024 + lane * 16), S);
;     return S;
; }
; template <class MaskF>
; DI void attn_rest(const f32x16& S, LAS unsigned char* LV, int lane, f32x16& O0, f32x16& O1, float& m_run, float& l_run, const MaskF& maskf) {
;     const int h = lane >> 5;
;     float sv[16]; float mx = -1e30f;
; #pragma unroll
;     for (int r = 0; r < 16; ++r) { sv[r] = maskf((r & 3) + 8 * (r >> 2), S[r]); mx = fmaxf(mx, sv[r]); }
;     mx = fmaxf(mx, shx(mx, 32));
;     if (__builtin_amdgcn_ballot_w64(mx > m_run) != 0ull) {
;         const float mn = fmaxf(m_run, mx);
;         const float alpha = fexp2(m_run - mn);
;         m_run = mn; l_run *= alpha;
; #pragma unroll
;         for (int i = 0; i < 16; ++i) { O0[i] *= alpha; O1[i] *= alpha; }
;     }
; template <class Desc>
; DI void attn_loop(const Desc& d, int ntiles, const bf16x8 (&qf)[4], LAS unsigned char* LV, int lane, bf16_t* orow) {
;     ...
;         const f32x16 Sb = attn_scores(LQ, lane, kB);
;         d.loadk(t + 3 < tl ? t + 3 : tl, kB);
;         attn_store_v(LV, lane, vN);
;         d.loadv(t + 2 < tl ? t + 2 : tl, vN);
;         d.rest(t + 1, Sb, LV, lane, O0, O1, m_run, l_run);
.LBB0_323:
	s_or_b64 exec, exec, s[58:59]
	s_min_u32 s40, s44, 29
	s_cmp_lt_u32 s44, 25
	s_cselect_b32 s41, 2, 4
	s_cselect_b32 s49, s48, 0xffffffe4
	s_waitcnt vmcnt(11) lgkmcnt(0)
	v_mfma_f32_32x32x16_bf16 v[2:17], v[80:83], v[236:239], 0
	s_cmp_lt_u32 s44, 17
	s_cselect_b32 s49, 0, s49
	s_cselect_b32 s41, 0, s41
	s_add_i32 s40, s40, s49
	s_lshl_b32 s40, s40, 5
	s_lshr_b32 s49, 0x1000, s41
	s_waitcnt vmcnt(10) lgkmcnt(0)
	v_mfma_f32_32x32x16_bf16 v[2:17], v[42:45], v[240:243], v[2:17]
	s_addk_i32 s40, 0x60
	s_add_i32 s49, s49, -1
	v_bfe_u32 v0, v137, 0, s41
	s_xor_b64 s[38:39], s[38:39], -1
	s_waitcnt vmcnt(9) lgkmcnt(0)
	v_mfma_f32_32x32x16_bf16 v[2:17], v[38:41], v[244:247], v[2:17]
	s_waitcnt vmcnt(8) lgkmcnt(0)
	v_mfma_f32_32x32x16_bf16 v[2:17], v[30:33], v[248:251], v[2:17]
	v_lshrrev_b32_e32 v30, s41, v151
	v_add3_u32 v30, v147, v30, s40
	v_min_u32_e32 v31, s49, v30
	v_cmp_lt_i32_e32 vcc, -1, v30
	s_nop 1
	v_cndmask_b32_e32 v30, 0, v31, vcc
	v_lshl_add_u32 v0, v30, s41, v0
	v_lshl_add_u64 v[30:31], v[46:47], 0, v[0:1]
	v_mad_u64_u32 v[32:33], s[40:41], v30, s90, v[140:141]
	v_mad_u32_u24 v33, v31, s90, v33
	global_load_dwordx4 v[80:83], v[32:33], off
	global_load_dwordx4 v[42:45], v[32:33], off offset:32
	global_load_dwordx4 v[38:41], v[32:33], off offset:64
	s_nop 0
	global_load_dwordx4 v[30:33], v[32:33], off offset:96
	s_waitcnt vmcnt(7)
	ds_write_b128 v143, v[84:87] offset:16384
	s_waitcnt vmcnt(6)
	ds_write_b128 v143, v[88:91] offset:17920
	s_waitcnt vmcnt(5)
	ds_write_b128 v143, v[92:95] offset:19456
	s_waitcnt vmcnt(4)
	ds_write_b128 v143, v[96:99] offset:20992
	v_or_b32_e32 v88, v163, v123
	v_min_u32_e32 v0, s47, v88
	v_cmp_lt_i32_e32 vcc, -1, v163
	s_nop 1
	v_cndmask_b32_e32 v0, 0, v0, vcc
	v_lshl_add_u32 v0, v0, s46, v162
	v_lshl_add_u64 v[84:85], v[46:47], 0, v[0:1]
	v_add_u32_e32 v0, 8, v88
	v_mad_u64_u32 v[86:87], s[40:41], v84, s90, v[138:139]
	v_min_u32_e32 v84, s47, v0
	v_cmp_lt_i32_e32 vcc, -1, v0
	v_mad_u32_u24 v87, v85, s90, v87
	global_load_dwordx4 v[96:99], v[86:87], off
	v_cndmask_b32_e32 v0, 0, v84, vcc
	v_lshl_add_u32 v0, v0, s46, v162
	v_lshl_add_u64 v[84:85], v[46:47], 0, v[0:1]
	v_add_u32_e32 v0, 16, v88
	v_mad_u64_u32 v[86:87], s[40:41], v84, s90, v[138:139]
	v_min_u32_e32 v84, s47, v0
	v_cmp_lt_i32_e32 vcc, -1, v0
	v_mad_u32_u24 v87, v85, s90, v87
	global_load_dwordx4 v[100:103], v[86:87], off
	v_cndmask_b32_e32 v0, 0, v84, vcc
	v_lshl_add_u32 v0, v0, s46, v162
	v_lshl_add_u64 v[84:85], v[46:47], 0, v[0:1]
	v_add_u32_e32 v0, 24, v88
	v_mad_u64_u32 v[86:87], s[40:41], v84, s90, v[138:139]
	v_min_u32_e32 v84, s47, v0
	v_cmp_lt_i32_e32 vcc, -1, v0
	v_mad_u32_u24 v87, v85, s90, v87
	global_load_dwordx4 v[104:107], v[86:87], off
	v_cndmask_b32_e32 v0, 0, v84, vcc
	v_lshl_add_u32 v0, v0, s46, v162
	v_lshl_add_u64 v[84:85], v[46:47], 0, v[0:1]
	v_mad_u64_u32 v[86:87], s[40:41], v84, s90, v[138:139]
	v_mad_u32_u24 v87, v85, s90, v87
	global_load_dwordx4 v[108:111], v[86:87], off
	v_subrev_u32_e32 v0, 32, v159
	v_cmp_ge_i32_e32 vcc, s45, v0
	s_and_b64 s[38:39], s[38:39], vcc
	s_and_saveexec_b64 s[40:41], s[38:39]
	s_xor_b64 s[38:39], exec, s[40:41]
	s_cbranch_execz .LBB0_327
	v_sub_u32_e32 v0, v159, v164
	v_add_u32_e32 v91, v0, v114
	v_cmp_gt_u32_e32 vcc, s82, v91
	v_add_u32_e32 v0, 1, v91
	s_nop 0
	v_cndmask_b32_e32 v90, v229, v2, vcc
	v_cmp_gt_u32_e32 vcc, s82, v0
	v_add_u32_e32 v2, 2, v91
	s_nop 0
	v_cndmask_b32_e32 v89, v229, v3, vcc
	v_cmp_gt_u32_e32 vcc, s82, v2
	v_add_u32_e32 v2, 3, v91
	v_max3_f32 v0, v90, s83, v89
	v_cndmask_b32_e32 v88, v229, v4, vcc
	v_cmp_gt_u32_e32 vcc, s82, v2
	v_add_u32_e32 v2, 8, v91
	v_add_u32_e32 v3, 25, v91
	v_cndmask_b32_e32 v87, v229, v5, vcc
	v_cmp_gt_u32_e32 vcc, s82, v2
	v_add_u32_e32 v2, 9, v91
	v_max3_f32 v0, v0, v88, v87
	v_cndmask_b32_e32 v86, v229, v6, vcc
	v_cmp_gt_u32_e32 vcc, s82, v2
	v_add_u32_e32 v2, 10, v91
	v_add_u32_e32 v5, 27, v91
	v_cndmask_b32_e32 v85, v229, v7, vcc
	v_cmp_gt_u32_e32 vcc, s82, v2
	v_add_u32_e32 v2, 11, v91
	v_max3_f32 v0, v0, v86, v85
	v_cndmask_b32_e32 v84, v229, v8, vcc
	v_cmp_gt_u32_e32 vcc, s82, v2
	v_add_u32_e32 v2, 16, v91
	s_nop 0
	v_cndmask_b32_e32 v9, v229, v9, vcc
	v_cmp_gt_u32_e32 vcc, s82, v2
	v_add_u32_e32 v2, 17, v91
	v_max3_f32 v0, v0, v84, v9
	v_cndmask_b32_e32 v8, v229, v10, vcc
	v_cmp_gt_u32_e32 vcc, s82, v2
	s_nop 1
	v_cndmask_b32_e32 v7, v229, v11, vcc
	v_max3_f32 v2, v0, v8, v7
	v_add_u32_e32 v0, 18, v91
	v_cmp_gt_u32_e32 vcc, s82, v0
	v_add_u32_e32 v0, 19, v91
	v_mov_b32_e32 v11, v205
	v_cndmask_b32_e32 v6, v229, v12, vcc
	v_cmp_gt_u32_e32 vcc, s82, v0
	s_nop 0
	v_lshlrev_b32_e32 v11, 2, v11
	v_cndmask_b32_e32 v0, v229, v13, vcc
	v_max3_f32 v4, v2, v6, v0
	v_add_u32_e32 v2, 24, v91
	v_cmp_gt_u32_e32 vcc, s82, v2
	v_xor_b32_e32 v11, 0x80, v11
	s_nop 0
	v_cndmask_b32_e32 v2, v229, v14, vcc
	v_cmp_gt_u32_e32 vcc, s82, v3
	s_nop 1
	v_cndmask_b32_e32 v3, v229, v15, vcc
	v_max3_f32 v10, v4, v2, v3
	v_add_u32_e32 v4, 26, v91
	v_cmp_gt_u32_e32 vcc, s82, v4
	s_nop 1
	v_cndmask_b32_e32 v4, v229, v16, vcc
	v_cmp_gt_u32_e32 vcc, s82, v5
	s_nop 1
	v_cndmask_b32_e32 v5, v229, v17, vcc
	v_max3_f32 v10, v10, v4, v5
	ds_bpermute_b32 v11, v11, v10
	s_waitcnt lgkmcnt(0)
	v_max_f32_e32 v11, v11, v11
	v_max_f32_e32 v10, v10, v11
	v_cmp_gt_f32_e32 vcc, v10, v133
	s_cbranch_vccz .LBB0_326
	v_max_f32_e32 v10, v10, v10
	v_max_f32_e32 v11, v133, v133
	v_max_f32_e32 v11, v11, v10
	v_sub_f32_e32 v10, v133, v11
	v_exp_f32_e32 v10, v10
	v_mov_b32_e32 v133, v11
	v_mul_f32_e32 v165, v165, v10
	v_pk_mul_f32 v[62:63], v[62:63], v[10:11] op_sel_hi:[1,0]
	v_pk_mul_f32 v[60:61], v[60:61], v[10:11] op_sel_hi:[1,0]
	v_pk_mul_f32 v[58:59], v[58:59], v[10:11] op_sel_hi:[1,0]
	v_pk_mul_f32 v[56:57], v[56:57], v[10:11] op_sel_hi:[1,0]
	v_pk_mul_f32 v[54:55], v[54:55], v[10:11] op_sel_hi:[1,0]
	v_pk_mul_f32 v[52:53], v[52:53], v[10:11] op_sel_hi:[1,0]
	v_pk_mul_f32 v[50:51], v[50:51], v[10:11] op_sel_hi:[1,0]
	v_pk_mul_f32 v[48:49], v[48:49], v[10:11] op_sel_hi:[1,0]
	v_pk_mul_f32 v[78:79], v[78:79], v[10:11] op_sel_hi:[1,0]
	v_pk_mul_f32 v[76:77], v[76:77], v[10:11] op_sel_hi:[1,0]
	v_pk_mul_f32 v[74:75], v[74:75], v[10:11] op_sel_hi:[1,0]
	v_pk_mul_f32 v[72:73], v[72:73], v[10:11] op_sel_hi:[1,0]
	v_pk_mul_f32 v[70:71], v[70:71], v[10:11] op_sel_hi:[1,0]
	v_pk_mul_f32 v[68:69], v[68:69], v[10:11] op_sel_hi:[1,0]
	v_pk_mul_f32 v[66:67], v[66:67], v[10:11] op_sel_hi:[1,0]
	v_pk_mul_f32 v[64:65], v[64:65], v[10:11] op_sel_hi:[1,0]

; #define LAS __attribute__((address_space(3)))
; DI float fexp2(float x) { return __builtin_amdgcn_exp2f(x); }
; DI float shx(float v, int o) { int l = (int)__builtin_amdgcn_mbcnt_hi(~0u, __builtin_amdgcn_mbcnt_lo(~0u, 0u)); asm volatile("" : "+v"(l)); return __int_as_float(__builtin_amdgcn_ds_bpermute((l ^ o) << 2, __float_as_int(v))); }
;     DI void rest(int t, const f32x16& S, LAS unsigned char* LV, int ln, f32x16& O0, f32x16& O1, float& m_run, float& l_run) const { attn_rest(S, LV, ln, O0, O1, m_run, l_run, mask(t)); }
; template <class MaskF>
; DI void attn_rest(const f32x16& S, LAS unsigned char* LV, int lane, f32x16& O0, f32x16& O1, float& m_run, float& l_run, const MaskF& maskf) {
;     const int h = lane >> 5;
;     float sv[16]; float mx = -1e30f;
; #pragma unroll
;     for (int r = 0; r < 16; ++r) { sv[r] = maskf((r & 3) + 8 * (r >> 2), S[r]); mx = fmaxf(mx, sv[r]); }
;     mx = fmaxf(mx, shx(mx, 32));
;     if (__builtin_amdgcn_ballot_w64(mx > m_run) != 0ull) {
;         const float mn = fmaxf(m_run, mx);
;         const float alpha = fexp2(m_run - mn);
;         m_run = mn; l_run *= alpha;
; #pragma unroll
;         for (int i = 0; i < 16; ++i) { O0[i] *= alpha; O1[i] *= alpha; }
;     }
; template <class Desc>
; DI void attn_loop(const Desc& d, int ntiles, const bf16x8 (&qf)[4], LAS unsigned char* LV, int lane, bf16_t* orow) {
;     ...
;     if (ntiles & 1) {
;         const f32x16 Sa = attn_scores(LQ, lane, kA);
;         attn_store_v(LV, lane, vN);
;         d.rest(tl, Sa, LV, lane, O0, O1, m_run, l_run);
.LBB0_330:
	s_waitcnt vmcnt(7) lgkmcnt(0)
	v_mfma_f32_32x32x16_bf16 v[80:95], v[34:37], v[236:239], 0
	s_waitcnt lgkmcnt(0)
	v_mfma_f32_32x32x16_bf16 v[80:95], v[26:29], v[240:243], v[80:95]
	s_waitcnt lgkmcnt(0)
	v_mfma_f32_32x32x16_bf16 v[80:95], v[22:25], v[244:247], v[80:95]
	s_waitcnt vmcnt(3)
	ds_write_b128 v143, v[96:99] offset:16384
	s_waitcnt vmcnt(2)
	ds_write_b128 v143, v[100:103] offset:17920
	s_waitcnt vmcnt(1)
	ds_write_b128 v143, v[104:107] offset:19456
	s_waitcnt vmcnt(0)
	ds_write_b128 v143, v[108:111] offset:20992
	s_waitcnt lgkmcnt(4)
	v_mfma_f32_32x32x16_bf16 v[80:95], v[18:21], v[248:251], v[80:95]
	s_and_saveexec_b64 s[38:39], s[0:1]
	v_readlane_b32 s46, v255, 29
	s_xor_b64 s[38:39], exec, s[38:39]
	v_readlane_b32 s47, v255, 30
	s_mov_b32 s49, 0x800000
	s_cbranch_execz .LBB0_334
	s_nop 5
	v_cndmask_b32_e64 v96, v229, v80, s[4:5]
	v_cndmask_b32_e64 v81, v229, v81, s[6:7]
	v_max3_f32 v0, v96, s83, v81
	v_cndmask_b32_e64 v80, v229, v82, s[8:9]
	v_cndmask_b32_e64 v15, v229, v83, s[10:11]
	v_max3_f32 v0, v0, v80, v15
	v_cndmask_b32_e64 v14, v229, v84, s[12:13]
	v_cndmask_b32_e64 v13, v229, v85, s[14:15]
	v_max3_f32 v0, v0, v14, v13
	v_cndmask_b32_e64 v12, v229, v86, s[16:17]
	v_cndmask_b32_e64 v11, v229, v87, s[18:19]
	v_max3_f32 v0, v0, v12, v11
	v_cndmask_b32_e64 v10, v229, v88, s[20:21]
	v_cndmask_b32_e64 v9, v229, v89, s[22:23]
	v_max3_f32 v0, v0, v10, v9
	v_cndmask_b32_e64 v6, v229, v90, s[24:25]
	v_cndmask_b32_e64 v5, v229, v91, s[26:27]
	v_mov_b32_e32 v8, v205
	v_max3_f32 v0, v0, v6, v5
	v_cndmask_b32_e64 v4, v229, v92, s[28:29]
	v_cndmask_b32_e64 v3, v229, v93, s[30:31]
	v_max3_f32 v7, v0, v4, v3
	v_cndmask_b32_e64 v2, v229, v94, s[34:35]
	v_cndmask_b32_e64 v0, v229, v95, s[36:37]
	v_lshlrev_b32_e32 v8, 2, v8
	v_max3_f32 v7, v7, v2, v0
	v_xor_b32_e32 v8, 0x80, v8
	ds_bpermute_b32 v8, v8, v7
	v_mov_b64_e32 v[32:33], v[64:65]
	v_mov_b64_e32 v[16:17], v[48:49]
	v_mov_b64_e32 v[34:35], v[66:67]
	v_mov_b64_e32 v[36:37], v[68:69]
	s_waitcnt lgkmcnt(0)
	v_max_f32_e32 v8, v8, v8
	v_max_f32_e32 v82, v7, v8
	v_cmp_gt_f32_e32 vcc, v82, v133
	v_mov_b32_e32 v7, v160
	v_mov_b64_e32 v[38:39], v[70:71]
	v_mov_b64_e32 v[40:41], v[72:73]
	v_mov_b64_e32 v[42:43], v[74:75]
	v_mov_b64_e32 v[44:45], v[76:77]
	v_mov_b64_e32 v[46:47], v[78:79]
	v_mov_b64_e32 v[18:19], v[50:51]
	v_mov_b64_e32 v[20:21], v[52:53]
	v_mov_b64_e32 v[22:23], v[54:55]
	v_mov_b64_e32 v[24:25], v[56:57]
	v_mov_b64_e32 v[26:27], v[58:59]
	v_mov_b64_e32 v[28:29], v[60:61]
	v_mov_b64_e32 v[30:31], v[62:63]
	v_mov_b32_e32 v8, v133
	s_cbranch_vccz .LBB0_333
	v_max_f32_e32 v7, v82, v82
	v_max_f32_e32 v8, v133, v133
	v_max_f32_e32 v8, v8, v7
	v_sub_f32_e32 v7, v133, v8
	v_exp_f32_e32 v32, v7
	s_nop 0
	v_mul_f32_e32 v7, v160, v32
	v_pk_mul_f32 v[30:31], v[62:63], v[32:33] op_sel_hi:[1,0]
	v_pk_mul_f32 v[28:29], v[60:61], v[32:33] op_sel_hi:[1,0]
	v_pk_mul_f32 v[26:27], v[58:59], v[32:33] op_sel_hi:[1,0]
	v_pk_mul_f32 v[24:25], v[56:57], v[32:33] op_sel_hi:[1,0]
	v_pk_mul_f32 v[22:23], v[54:55], v[32:33] op_sel_hi:[1,0]
	v_pk_mul_f32 v[20:21], v[52:53], v[32:33] op_sel_hi:[1,0]
	v_pk_mul_f32 v[18:19], v[50:51], v[32:33] op_sel_hi:[1,0]
	v_pk_mul_f32 v[16:17], v[48:49], v[32:33] op_sel_hi:[1,0]
	v_pk_mul_f32 v[46:47], v[78:79], v[32:33] op_sel_hi:[1,0]
	v_pk_mul_f32 v[44:45], v[76:77], v[32:33] op_sel_hi:[1,0]
	v_pk_mul_f32 v[42:43], v[74:75], v[32:33] op_sel_hi:[1,0]
	v_pk_mul_f32 v[40:41], v[72:73], v[32:33] op_sel_hi:[1,0]
	v_pk_mul_f32 v[38:39], v[70:71], v[32:33] op_sel_hi:[1,0]
	v_pk_mul_f32 v[36:37], v[68:69], v[32:33] op_sel_hi:[1,0]
	v_pk_mul_f32 v[34:35], v[66:67], v[32:33] op_sel_hi:[1,0]
	v_pk_mul_f32 v[32:33], v[64:65], v[32:33] op_sel_hi:[1,0]

; #define LAS __attribute__((address_space(3)))
;     DI void loadk(int t, bf16x8 (&kn)[4]) const { attn_load_k(P, tokbase, EIN, kcol, 1, 0, SEQ, (rsA + t) * 64 + c0, lane, kn); }
;     DI void loadv(int t, bf16x8 (&vn)[4]) const { attn_load_v(P, tokbase, EIN, vcol, 1, 0, SEQ, (rsA + t) * 64 + c0, lane, vn); }
;     DI void loadk(int T, bf16x8 (&kn)[4]) const { const int sh = sh_of(T); attn_load_k(P, tokbase, EIN, kcol, 1 << sh, r & ((1 << sh) - 1), SEQ >> sh, m0_of(T), lane, kn); }
;     DI void loadv(int T, bf16x8 (&vn)[4]) const { const int sh = sh_of(T); attn_load_v(P, tokbase, EIN, vcol, 1 << sh, r & ((1 << sh) - 1), SEQ >> sh, m0_of(T), lane, vn); }
; template <class Desc>
; DI void attn_loop(const Desc& d, int ntiles, const bf16x8 (&qf)[4], LAS unsigned char* LV, int lane, bf16_t* orow) {
;     LAS unsigned char* LQ = LV + ATT_V_BYTES;
;     asm volatile("" ::: "memory");
; #pragma unroll
;     for (int c = 0; c < 4; ++c) lds_w128(LQ, c * 1024 + lane * 16, qf[c]);
;     asm volatile("" ::: "memory");
;     f32x16 O0, O1;
; #pragma unroll
;     for (int i = 0; i < 16; ++i) { O0[i] = 0.f; O1[i] = 0.f; }
;     float m_run = -1e30f, l_run = 0.f;
;     bf16x8 kA[4], kB[4], vN[4];
;     const int tl = ntiles - 1;
;     d.loadk(0, kA); d.loadv(0, vN); d.loadk(1 < tl ? 1 : tl, kB);
; DI void na_item(int item, const bf16_t* P, bf16_t* Oo, LAS float* rpbL, LAS unsigned char* LV, int lane) {
;     const int cb = item & 3, rp = (item >> 2) & 31, head = (item >> 7) & 7, seq = item >> 10;
;     const size_t tokbase = (size_t)seq * SEQ;
;     const int h = lane >> 5, j = lane & 31, qr = 2 * rp + (j >> 4), qc = 16 * cb + (j & 15), tq = qr * 64 + qc;
;     bf16x8 qf[4];
;     { const bf16_t* qp = P + (tokbase + tq) * EIN + head * 64 + 8 * h;
; #pragma unroll
;       for (int c = 0; c < 4; ++c) qf[c] = *(const bf16x8*)(qp + 16 * c); }
;     int rs = qr - 4; rs = rs < 0 ? 0 : (rs > 56 ? 56 : rs);
;     int cs = qc - 8; cs = cs < 0 ? 0 : (cs > 48 ? 48 : cs);
;     int rsA = 2 * rp - 4; rsA = rsA < 0 ? 0 : (rsA > 56 ? 56 : rsA);
;     int rsB = 2 * rp - 3; rsB = rsB < 0 ? 0 : (rsB > 56 ? 56 : rsB);
;     const int c0 = cb == 0 ? 0 : (cb == 1 ? 8 : (cb == 2 ? 24 : 32));
;     const NaDesc d{P, tokbase, rpbL + head * 465, lane, 512 + head * 64, 1024 + head * 64, rsA, c0, qr, qc, rs, cs};
;     attn_loop(d, rsB + 8 - rsA, qf, LV, lane, Oo + (tokbase + tq) * D + head * 64);
.LBB0_344:
	s_or_b64 exec, exec, s[38:39]
	v_med3_u32 v21, v19, 4, 60
	v_add_u32_e32 v165, -4, v21
	s_waitcnt vmcnt(3)
	v_mov_b64_e32 v[236:237], v[2:3]
	v_mov_b64_e32 v[238:239], v[4:5]
	s_waitcnt vmcnt(2)
	v_mov_b64_e32 v[240:241], v[6:7]
	v_mov_b64_e32 v[242:243], v[8:9]
	s_waitcnt vmcnt(1)
	v_mov_b64_e32 v[244:245], v[10:11]
	v_mov_b64_e32 v[246:247], v[12:13]
	s_waitcnt vmcnt(0)
	v_mov_b64_e32 v[248:249], v[14:15]
	v_mov_b64_e32 v[250:251], v[16:17]
	v_lshl_or_b32 v2, v165, 6, v135
	v_add_u32_e32 v4, v2, v121
	v_mov_b32_e32 v5, v1
	v_lshl_add_u64 v[4:5], v[138:139], 0, v[4:5]
	v_mov_b64_e32 v[6:7], s[86:87]
	v_lshlrev_b32_e32 v20, 6, v18
	v_mad_u64_u32 v[6:7], s[38:39], v4, s90, v[6:7]
	v_mad_i32_i24 v7, v5, s90, v7
	v_lshlrev_b32_e32 v136, 1, v20
	v_mov_b32_e32 v137, v1
	v_lshl_add_u64 v[4:5], v[6:7], 0, v[136:137]
	v_lshl_add_u64 v[4:5], v[4:5], 0, v[0:1]
	global_load_dwordx4 v[76:79], v[4:5], off offset:1024
	global_load_dwordx4 v[72:75], v[4:5], off offset:1056
	global_load_dwordx4 v[68:71], v[4:5], off offset:1088
	global_load_dwordx4 v[64:67], v[4:5], off offset:1120
	v_or_b32_e32 v4, v2, v123
	v_mov_b32_e32 v5, v1
	v_lshl_add_u64 v[140:141], v[130:131], 0, v[136:137]
	v_lshl_add_u64 v[6:7], v[138:139], 0, v[4:5]
	v_mad_u64_u32 v[8:9], s[38:39], v6, s90, v[140:141]
	v_mad_i32_i24 v9, v7, s90, v9
	v_add_u32_e32 v6, 8, v4
	v_mov_b32_e32 v7, v1
	v_lshl_add_u64 v[6:7], v[138:139], 0, v[6:7]
	v_mad_u64_u32 v[10:11], s[38:39], v6, s90, v[140:141]
	v_mad_i32_i24 v11, v7, s90, v11
	v_add_u32_e32 v6, 16, v4
	v_mov_b32_e32 v7, v1
	v_lshl_add_u64 v[6:7], v[138:139], 0, v[6:7]
	v_add_u32_e32 v4, 24, v4
	global_load_dwordx4 v[96:99], v[8:9], off offset:2048
	global_load_dwordx4 v[100:103], v[10:11], off offset:2048
	v_mad_u64_u32 v[8:9], s[38:39], v6, s90, v[140:141]
	v_lshl_add_u64 v[4:5], v[138:139], 0, v[4:5]
	v_mad_i32_i24 v9, v7, s90, v9
	v_mad_u64_u32 v[6:7], s[38:39], v4, s90, v[140:141]
	v_mad_i32_i24 v7, v5, s90, v7
	global_load_dwordx4 v[104:107], v[8:9], off offset:2048
	global_load_dwordx4 v[108:111], v[6:7], off offset:2048
	v_med3_u32 v161, v19, 3, 59
	v_max_u32_e32 v162, 4, v160
	v_add_u32_e32 v167, 5, v161
	v_mov_b32_e32 v30, v1
	v_mov_b32_e32 v31, v1
	v_min_u32_e32 v3, 60, v162
	v_mul_u32_u24_e32 v166, 0x744, v18
	v_sub_u32_e32 v168, v167, v165
	v_mov_b32_e32 v16, v1
	v_mov_b32_e32 v17, v1
	v_mov_b32_e32 v18, v1
	v_mov_b32_e32 v19, v1
	v_mov_b32_e32 v20, v1
	v_mov_b32_e32 v21, v1
	v_mov_b32_e32 v22, v1
	v_mov_b32_e32 v23, v1
	v_mov_b32_e32 v24, v1
	v_mov_b32_e32 v25, v1
	v_mov_b32_e32 v26, v1
	v_mov_b32_e32 v27, v1
	v_mov_b32_e32 v28, v1
	v_mov_b32_e32 v29, v1
	v_mov_b64_e32 v[46:47], v[30:31]
	v_add_u32_e32 v163, -4, v3
	v_cmp_lt_i32_e32 vcc, 1, v168
	v_mov_b32_e32 v159, 0
	v_mov_b32_e32 v133, 0xf149f2ca
	v_or_b32_e32 v164, v135, v114
	v_mov_b64_e32 v[44:45], v[28:29]
	v_mov_b64_e32 v[42:43], v[26:27]
	v_mov_b64_e32 v[40:41], v[24:25]
	v_mov_b64_e32 v[38:39], v[22:23]
	v_mov_b64_e32 v[36:37], v[20:21]
	v_mov_b64_e32 v[34:35], v[18:19]
	v_mov_b64_e32 v[32:33], v[16:17]
	s_and_saveexec_b64 s[96:97], vcc
	s_cbranch_execz .LBB0_352
	v_add_u32_e32 v4, v149, v2
	v_mov_b32_e32 v5, v1
	v_lshl_add_u64 v[4:5], v[138:139], 0, v[4:5]
	v_mov_b64_e32 v[6:7], s[86:87]
	v_mad_u64_u32 v[6:7], s[38:39], v4, s90, v[6:7]
	v_mad_i32_i24 v7, v5, s90, v7
	v_lshl_add_u64 v[4:5], v[6:7], 0, v[136:137]
	v_lshl_add_u64 v[4:5], v[4:5], 0, v[0:1]
	global_load_dwordx4 v[80:83], v[4:5], off offset:1120
	global_load_dwordx4 v[84:87], v[4:5], off offset:1088
	global_load_dwordx4 v[88:91], v[4:5], off offset:1056
	global_load_dwordx4 v[92:95], v[4:5], off offset:1024
	v_bfe_u32 v0, v113, 2, 5
	v_lshlrev_b32_e32 v2, 1, v0
	v_med3_u32 v170, v2, 4, 60
	v_mul_u32_u24_e32 v2, 0x7c, v170
	v_lshl_add_u64 v[142:143], v[116:117], 0, v[136:137]
	v_add_u32_e32 v137, 4, v3
	v_lshlrev_b32_e32 v3, 2, v135
	v_mul_u32_u24_e32 v0, 0xf8, v0
	v_add3_u32 v2, v166, v2, v3
	v_lshlrev_b32_e32 v4, 6, v170
	v_sub_u32_e32 v0, v2, v0
	v_mov_b32_e32 v14, v1
	v_mov_b32_e32 v15, v1
	v_add_u32_e32 v173, v156, v0
	v_add3_u32 v174, v157, v135, v4
	v_mov_b32_e32 v0, v1
	v_mov_b32_e32 v2, v1
	v_mov_b32_e32 v3, v1
	v_mov_b32_e32 v4, v1
	v_mov_b32_e32 v5, v1
	v_mov_b32_e32 v6, v1
	v_mov_b32_e32 v7, v1
	v_mov_b32_e32 v8, v1
	v_mov_b32_e32 v9, v1
	v_mov_b32_e32 v10, v1
	v_mov_b32_e32 v11, v1
	v_mov_b32_e32 v12, v1
	v_mov_b32_e32 v13, v1
	v_mov_b64_e32 v[30:31], v[14:15]
	v_mov_b64_e32 v[46:47], v[14:15]
	v_add_u32_e32 v169, -1, v168
	v_sub_u32_e32 v171, v164, v155
	v_add_u32_e32 v172, v135, v121
	v_mov_b32_e32 v159, 0
	v_mov_b32_e32 v133, 0xf149f2ca
	s_mov_b32 s44, 3
	s_mov_b64 s[58:59], 0
	v_mov_b64_e32 v[28:29], v[12:13]
	v_mov_b64_e32 v[26:27], v[10:11]
	v_mov_b64_e32 v[24:25], v[8:9]
	v_mov_b64_e32 v[22:23], v[6:7]
	v_mov_b64_e32 v[20:21], v[4:5]
	v_mov_b64_e32 v[18:19], v[2:3]
	v_mov_b64_e32 v[16:17], v[0:1]
	v_mov_b64_e32 v[44:45], v[12:13]
	v_mov_b64_e32 v[42:43], v[10:11]
	v_mov_b64_e32 v[40:41], v[8:9]
	v_mov_b64_e32 v[38:39], v[6:7]
	v_mov_b64_e32 v[36:37], v[4:5]
	v_mov_b64_e32 v[34:35], v[2:3]
	v_mov_b64_e32 v[32:33], v[0:1]
	s_branch .LBB0_347

; #define LAS __attribute__((address_space(3)))
; DI float fexp2(float x) { return __builtin_amdgcn_exp2f(x); }
; DI float shx(float v, int o) { int l = (int)__builtin_amdgcn_mbcnt_hi(~0u, __builtin_amdgcn_mbcnt_lo(~0u, 0u)); asm volatile("" : "+v"(l)); return __int_as_float(__builtin_amdgcn_ds_bpermute((l ^ o) << 2, __float_as_int(v))); }
; DI f32x16 mfma32(bf16x8 a, bf16x8 b, f32x16 c) { return __builtin_amdgcn_mfma_f32_32x32x16_bf16(a, b, c, 0, 0, 0); }
;     DI void loadk(int t, bf16x8 (&kn)[4]) const { attn_load_k(P, tokbase, EIN, kcol, 1, 0, SEQ, (rsA + t) * 64 + c0, lane, kn); }
;     DI void loadv(int t, bf16x8 (&vn)[4]) const { attn_load_v(P, tokbase, EIN, vcol, 1, 0, SEQ, (rsA + t) * 64 + c0, lane, vn); }
;     DI void rest(int t, const f32x16& S, LAS unsigned char* LV, int ln, f32x16& O0, f32x16& O1, float& m_run, float& l_run) const { attn_rest(S, LV, ln, O0, O1, m_run, l_run, mask(t)); }
; DI f32x16 attn_scores(LAS unsigned char* LQ, int lane, const bf16x8 (&kf)[4]) {
;     f32x16 S;
; #pragma unroll
;     for (int i = 0; i < 16; ++i) S[i] = 0.f;
; #pragma unroll
;     for (int c = 0; c < 4; ++c) S = mfma32(kf[c], lds_r128(LQ, c * 1024 + lane * 16), S);
;     return S;
; }
; template <class MaskF>
; DI void attn_rest(const f32x16& S, LAS unsigned char* LV, int lane, f32x16& O0, f32x16& O1, float& m_run, float& l_run, const MaskF& maskf) {
;     const int h = lane >> 5;
;     float sv[16]; float mx = -1e30f;
; #pragma unroll
;     for (int r = 0; r < 16; ++r) { sv[r] = maskf((r & 3) + 8 * (r >> 2), S[r]); mx = fmaxf(mx, sv[r]); }
;     mx = fmaxf(mx, shx(mx, 32));
;     if (__builtin_amdgcn_ballot_w64(mx > m_run) != 0ull) {
;         const float mn = fmaxf(m_run, mx);
;         const float alpha = fexp2(m_run - mn);
;         m_run = mn; l_run *= alpha;
; #pragma unroll
;         for (int i = 0; i < 16; ++i) { O0[i] *= alpha; O1[i] *= alpha; }
;     }
; template <class Desc>
; DI void attn_loop(const Desc& d, int ntiles, const bf16x8 (&qf)[4], LAS unsigned char* LV, int lane, bf16_t* orow) {
;     ...
;     for (int t = 0; t + 1 < ntiles; t += 2) {
;         const f32x16 Sa = attn_scores(LQ, lane, kA);
;         d.loadk(t + 2 < tl ? t + 2 : tl, kA);
;         attn_store_v(LV, lane, vN);
;         d.loadv(t + 1, vN);
;         d.rest(t, Sa, LV, lane, O0, O1, m_run, l_run);
.LBB0_347:
	s_add_i32 s38, s44, -1
	v_min_i32_e32 v0, s38, v169
	v_add_u32_e32 v0, v0, v165
	v_lshl_or_b32 v15, v0, 6, v135
	s_waitcnt vmcnt(11) lgkmcnt(0)
	v_mfma_f32_32x32x16_bf16 v[48:63], v[76:79], v[236:239], 0
	v_add_u32_e32 v0, v15, v121
	v_med3_i32 v0, v0, 0, v228
	v_or_b32_e32 v0, v138, v0
	v_add_u32_e32 v175, v125, v127
	v_add_u32_e32 v14, s44, v170
	s_waitcnt vmcnt(10) lgkmcnt(0)
	v_mfma_f32_32x32x16_bf16 v[48:63], v[72:75], v[240:243], v[48:63]
	s_waitcnt vmcnt(9) lgkmcnt(0)
	v_mfma_f32_32x32x16_bf16 v[48:63], v[68:71], v[244:247], v[48:63]
	s_waitcnt vmcnt(8) lgkmcnt(0)
	v_mfma_f32_32x32x16_bf16 v[48:63], v[64:67], v[248:251], v[48:63]
	v_mad_u64_u32 v[2:3], s[38:39], v0, s90, v[142:143]
	v_min_u32_e32 v0, 0xfff, v174
	v_mad_i32_i24 v3, v139, s90, v3
	v_or_b32_e32 v0, v138, v0
	global_load_dwordx4 v[76:79], v[2:3], off offset:1024
	global_load_dwordx4 v[72:75], v[2:3], off offset:1056
	global_load_dwordx4 v[68:71], v[2:3], off offset:1088
	global_load_dwordx4 v[64:67], v[2:3], off offset:1120
	v_mad_u64_u32 v[2:3], s[38:39], v0, s90, v[140:141]
	v_min_u32_e32 v0, 0xff7, v174
	v_add_u32_e32 v0, 8, v0
	v_lshl_add_u64 v[6:7], v[138:139], 0, v[0:1]
	v_min_u32_e32 v0, 0xfef, v174
	v_add_u32_e32 v0, 16, v0
	v_lshl_add_u64 v[10:11], v[138:139], 0, v[0:1]
	v_min_u32_e32 v0, 0xfe7, v174
	v_add_u32_e32 v0, 24, v0
	s_waitcnt vmcnt(7)
	ds_write_b128 v175, v[96:99] offset:16384
	s_waitcnt vmcnt(6)
	ds_write_b128 v175, v[100:103] offset:17920
	s_waitcnt vmcnt(5)
	ds_write_b128 v175, v[104:107] offset:19456
	s_waitcnt vmcnt(4)
	ds_write_b128 v175, v[108:111] offset:20992
	v_lshl_add_u64 v[96:97], v[138:139], 0, v[0:1]
	v_mad_u64_u32 v[8:9], s[38:39], v6, s90, v[140:141]
	v_mad_u64_u32 v[12:13], s[38:39], v10, s90, v[140:141]
	v_mad_u64_u32 v[98:99], s[38:39], v96, s90, v[140:141]
	v_mad_i32_i24 v3, v139, s90, v3
	v_mad_i32_i24 v9, v7, s90, v9
	v_mad_i32_i24 v13, v11, s90, v13
	v_mad_i32_i24 v99, v97, s90, v99
	global_load_dwordx4 v[2:5], v[2:3], off offset:2048
	ds_read2_b32 v[100:101], v173 offset1:1
	global_load_dwordx4 v[6:9], v[8:9], off offset:2048
	v_add_u32_e32 v0, -7, v14
	global_load_dwordx4 v[10:13], v[12:13], off offset:2048
	v_cmp_ge_u32_e32 vcc, v0, v163
	global_load_dwordx4 v[96:99], v[98:99], off offset:2048
	v_cmp_lt_u32_e64 s[38:39], v0, v137
	s_and_b64 vcc, vcc, s[38:39]
	v_cndmask_b32_e32 v102, v230, v171, vcc
	v_cmp_gt_u32_e32 vcc, 16, v102
	s_waitcnt lgkmcnt(0)
	v_add_f32_e32 v0, v48, v100
	v_cndmask_b32_e32 v48, v229, v0, vcc
	v_add_u32_e32 v0, 1, v102
	v_cmp_gt_u32_e32 vcc, 16, v0
	v_add_f32_e32 v0, v49, v101
	ds_read2_b32 v[100:101], v173 offset0:2 offset1:3
	v_add_u32_e32 v49, 2, v102
	v_cndmask_b32_e32 v0, v229, v0, vcc
	v_cmp_gt_u32_e32 vcc, 16, v49
	v_max3_f32 v103, v48, s83, v0
	s_waitcnt lgkmcnt(0)
	v_add_f32_e32 v49, v50, v100
	v_cndmask_b32_e32 v50, v229, v49, vcc
	v_add_u32_e32 v49, 3, v102
	v_cmp_gt_u32_e32 vcc, 16, v49
	v_add_f32_e32 v49, v51, v101
	ds_read2_b32 v[100:101], v173 offset0:8 offset1:9
	v_add_u32_e32 v51, 8, v102
	v_cndmask_b32_e32 v49, v229, v49, vcc
	v_cmp_gt_u32_e32 vcc, 16, v51
	v_max3_f32 v103, v103, v50, v49
	s_waitcnt lgkmcnt(0)
	v_add_f32_e32 v51, v52, v100
	v_cndmask_b32_e32 v52, v229, v51, vcc
	v_add_u32_e32 v51, 9, v102
	v_cmp_gt_u32_e32 vcc, 16, v51
	v_add_f32_e32 v51, v53, v101
	ds_read2_b32 v[100:101], v173 offset0:10 offset1:11
	v_add_u32_e32 v53, 10, v102
	v_cndmask_b32_e32 v51, v229, v51, vcc
	v_cmp_gt_u32_e32 vcc, 16, v53
	v_max3_f32 v103, v103, v52, v51
	s_waitcnt lgkmcnt(0)
	v_add_f32_e32 v53, v54, v100
	v_add_u32_e32 v54, 11, v102
	v_cndmask_b32_e32 v53, v229, v53, vcc
	v_cmp_gt_u32_e32 vcc, 16, v54
	v_add_f32_e32 v54, v55, v101
	ds_read2_b32 v[100:101], v173 offset0:16 offset1:17
	v_cndmask_b32_e32 v54, v229, v54, vcc
	v_cmp_lt_u32_e32 vcc, s54, v102
	v_max3_f32 v103, v103, v53, v54
	s_waitcnt lgkmcnt(0)
	v_add_f32_e32 v55, v56, v100
	v_cndmask_b32_e32 v56, v229, v55, vcc
	v_add_u32_e32 v55, 17, v102
	v_cmp_gt_u32_e32 vcc, 16, v55
	v_add_f32_e32 v55, v57, v101
	ds_read2_b32 v[100:101], v173 offset0:18 offset1:19
	v_add_u32_e32 v57, 18, v102
	v_cndmask_b32_e32 v55, v229, v55, vcc
	v_cmp_gt_u32_e32 vcc, 16, v57
	v_max3_f32 v103, v103, v56, v55
	s_waitcnt lgkmcnt(0)
	v_add_f32_e32 v57, v58, v100
	v_cndmask_b32_e32 v58, v229, v57, vcc
	v_add_u32_e32 v57, 19, v102
	v_cmp_gt_u32_e32 vcc, 16, v57
	v_add_f32_e32 v57, v59, v101
	ds_read2_b32 v[100:101], v173 offset0:24 offset1:25
	v_add_u32_e32 v59, 24, v102
	v_cndmask_b32_e32 v57, v229, v57, vcc
	v_cmp_gt_u32_e32 vcc, 16, v59
	v_max3_f32 v103, v103, v58, v57
	s_waitcnt lgkmcnt(0)
	v_add_f32_e32 v59, v60, v100
	v_add_u32_e32 v60, 25, v102
	v_cndmask_b32_e32 v59, v229, v59, vcc
	v_cmp_gt_u32_e32 vcc, 16, v60
	v_add_f32_e32 v60, v61, v101
	ds_read2_b32 v[100:101], v173 offset0:26 offset1:27
	v_add_u32_e32 v61, 26, v102
	v_cndmask_b32_e32 v60, v229, v60, vcc
	v_cmp_gt_u32_e32 vcc, 16, v61
	v_max3_f32 v103, v103, v59, v60
	s_waitcnt lgkmcnt(0)
	v_add_f32_e32 v61, v62, v100
	v_add_u32_e32 v62, 27, v102
	v_mov_b32_e32 v100, v205
	v_cndmask_b32_e32 v61, v229, v61, vcc
	v_cmp_gt_u32_e32 vcc, 16, v62
	v_add_f32_e32 v62, v63, v101
	s_nop 0
	v_cndmask_b32_e32 v62, v229, v62, vcc
	v_lshlrev_b32_e32 v100, 2, v100
	v_max3_f32 v63, v103, v61, v62
	v_xor_b32_e32 v100, 0x80, v100
	ds_bpermute_b32 v100, v100, v63
	s_waitcnt lgkmcnt(0)
	v_max_f32_e32 v100, v100, v100
	v_max_f32_e32 v63, v63, v100
	v_cmp_gt_f32_e32 vcc, v63, v133
	s_cbranch_vccz .LBB0_349
	v_max_f32_e32 v63, v63, v63
	v_max_f32_e32 v100, v133, v133
	v_max_f32_e32 v63, v100, v63
	v_sub_f32_e32 v100, v133, v63
	v_exp_f32_e32 v100, v100
	v_mov_b32_e32 v133, v63
	v_mul_f32_e32 v159, v159, v100
	v_pk_mul_f32 v[30:31], v[30:31], v[100:101] op_sel_hi:[1,0]
	v_pk_mul_f32 v[28:29], v[28:29], v[100:101] op_sel_hi:[1,0]
	v_pk_mul_f32 v[26:27], v[26:27], v[100:101] op_sel_hi:[1,0]
	v_pk_mul_f32 v[24:25], v[24:25], v[100:101] op_sel_hi:[1,0]
	v_pk_mul_f32 v[22:23], v[22:23], v[100:101] op_sel_hi:[1,0]
	v_pk_mul_f32 v[20:21], v[20:21], v[100:101] op_sel_hi:[1,0]
	v_pk_mul_f32 v[18:19], v[18:19], v[100:101] op_sel_hi:[1,0]
	v_pk_mul_f32 v[16:17], v[16:17], v[100:101] op_sel_hi:[1,0]
	v_pk_mul_f32 v[46:47], v[46:47], v[100:101] op_sel_hi:[1,0]
	v_pk_mul_f32 v[44:45], v[44:45], v[100:101] op_sel_hi:[1,0]
	v_pk_mul_f32 v[42:43], v[42:43], v[100:101] op_sel_hi:[1,0]
	v_pk_mul_f32 v[40:41], v[40:41], v[100:101] op_sel_hi:[1,0]
	v_pk_mul_f32 v[38:39], v[38:39], v[100:101] op_sel_hi:[1,0]
	v_pk_mul_f32 v[36:37], v[36:37], v[100:101] op_sel_hi:[1,0]
	v_pk_mul_f32 v[34:35], v[34:35], v[100:101] op_sel_hi:[1,0]
	v_pk_mul_f32 v[32:33], v[32:33], v[100:101] op_sel_hi:[1,0]
; DI float fexp2(float x) { return __builtin_amdgcn_exp2f(x); }
; DI s16x4 lds_tr(LAS unsigned char* L, int off) { return __builtin_amdgcn_ds_read_tr16_b64_v4i16((LAS s16x4*)(L + off)); }
; DI bf16x8 cat4(s16x4 lo, s16x4 hi) { return __builtin_shufflevector(lo, hi, 0, 1, 2, 3, 4, 5, 6, 7); }
; DI f32x16 mfma32(bf16x8 a, bf16x8 b, f32x16 c) { return __builtin_amdgcn_mfma_f32_32x32x16_bf16(a, b, c, 0, 0, 0); }
; DI bf16x8 pack8(const float* v) { u32x4 w; w.x = pack_bf16(v[0], v[1]); w.y = pack_bf16(v[2], v[3]); w.z = pack_bf16(v[4], v[5]); w.w = pack_bf16(v[6], v[7]); return __builtin_bit_cast(bf16x8, w); }
;     DI void loadk(int t, bf16x8 (&kn)[4]) const { attn_load_k(P, tokbase, EIN, kcol, 1, 0, SEQ, (rsA + t) * 64 + c0, lane, kn); }
;     DI void loadv(int t, bf16x8 (&vn)[4]) const { attn_load_v(P, tokbase, EIN, vcol, 1, 0, SEQ, (rsA + t) * 64 + c0, lane, vn); }
;     DI void rest(int t, const f32x16& S, LAS unsigned char* LV, int ln, f32x16& O0, f32x16& O1, float& m_run, float& l_run) const { attn_rest(S, LV, ln, O0, O1, m_run, l_run, mask(t)); }
; template <class MaskF>
; DI void attn_rest(const f32x16& S, LAS unsigned char* LV, int lane, f32x16& O0, f32x16& O1, float& m_run, float& l_run, const MaskF& maskf) {
;     ...
;     float ps = 0.f;
; #pragma unroll
;     for (int r = 0; r < 16; ++r) { const float p = fexp2(sv[r] - m_run); sv[r] = p; ps += p; }
;     l_run += ps;
;     const int i16 = lane & 15, q4 = i16 >> 2, p4 = i16 & 3, blk = (lane >> 4) & 1;
; #pragma unroll
;     for (int s = 0; s < 2; ++s) {
;         const bf16x8 pf = pack8(&sv[8 * s]);
;         const int r0 = 16 * s + 4 * h + q4, cb = 2 * (16 * blk + 4 * p4);
;         const s16x4 lo0 = lds_tr(LV, r0 * ATT_RSV + cb), hi0 = lds_tr(LV, (r0 + 8) * ATT_RSV + cb);
;         const s16x4 lo1 = lds_tr(LV, r0 * ATT_RSV + 64 + cb), hi1 = lds_tr(LV, (r0 + 8) * ATT_RSV + 64 + cb);
;         O0 = mfma32(cat4(lo0, hi0), pf, O0);
;         O1 = mfma32(cat4(lo1, hi1), pf, O1);
;     }
; template <class Desc>
; DI void attn_loop(const Desc& d, int ntiles, const bf16x8 (&qf)[4], LAS unsigned char* LV, int lane, bf16_t* orow) {
;     ...
;         const f32x16 Sb = attn_scores(LQ, lane, kB);
;         d.loadk(t + 3 < tl ? t + 3 : tl, kB);
;         attn_store_v(LV, lane, vN);
;         d.loadv(t + 2 < tl ? t + 2 : tl, vN);
;         d.rest(t + 1, Sb, LV, lane, O0, O1, m_run, l_run);
.LBB0_349:
	v_add_u32_e32 v176, -6, v14
	v_sub_f32_e32 v14, v48, v133
	v_exp_f32_e32 v14, v14
	v_sub_f32_e32 v0, v0, v133
	v_exp_f32_e32 v0, v0
	v_sub_f32_e32 v50, v50, v133
	v_exp_f32_e32 v50, v50
	v_sub_f32_e32 v49, v49, v133
	v_exp_f32_e32 v49, v49
	v_sub_f32_e32 v52, v52, v133
	v_add_f32_e32 v48, 0, v14
	v_exp_f32_e32 v52, v52
	v_sub_f32_e32 v51, v51, v133
	v_add_f32_e32 v48, v0, v48
	v_exp_f32_e32 v51, v51
	v_sub_f32_e32 v53, v53, v133
	v_add_f32_e32 v48, v50, v48
	v_exp_f32_e32 v53, v53
	v_sub_f32_e32 v54, v54, v133
	v_add_f32_e32 v48, v49, v48
	v_exp_f32_e32 v54, v54
	v_sub_f32_e32 v56, v56, v133
	v_add_f32_e32 v48, v52, v48
	v_exp_f32_e32 v63, v56
	v_sub_f32_e32 v55, v55, v133
	v_add_f32_e32 v48, v51, v48
	v_exp_f32_e32 v100, v55
	v_sub_f32_e32 v55, v58, v133
	v_add_f32_e32 v48, v53, v48
	v_exp_f32_e32 v101, v55
	v_sub_f32_e32 v55, v57, v133
	v_add_f32_e32 v48, v54, v48
	v_exp_f32_e32 v102, v55
	v_sub_f32_e32 v55, v59, v133
	v_add_f32_e32 v48, v63, v48
	v_exp_f32_e32 v103, v55
	v_sub_f32_e32 v55, v60, v133
	v_add_f32_e32 v48, v100, v48
	v_exp_f32_e32 v60, v55
	v_sub_f32_e32 v55, v61, v133
	v_add_f32_e32 v48, v101, v48
	v_exp_f32_e32 v61, v55
	v_sub_f32_e32 v55, v62, v133
	v_add_f32_e32 v48, v102, v48
	v_exp_f32_e32 v62, v55
	v_add_f32_e32 v48, v103, v48
	v_add_f32_e32 v48, v60, v48
	v_add_f32_e32 v48, v61, v48
	v_add_f32_e32 v48, v62, v48
	v_add_f32_e32 v159, v159, v48
	v_cvt_pk_bf16_f32 v48, v14, v0
	v_add_u32_e32 v14, v144, v145
	v_cvt_pk_bf16_f32 v49, v50, v49
	v_cvt_pk_bf16_f32 v50, v52, v51
	v_cvt_pk_bf16_f32 v51, v53, v54
	ds_read_b64_tr_b16 v[52:53], v14 offset:16384
	v_add_u32_e32 v0, v146, v129
	ds_read_b64_tr_b16 v[54:55], v0 offset:17920
	ds_read_b64_tr_b16 v[56:57], v0 offset:16448
	ds_read_b64_tr_b16 v[58:59], v0 offset:17984
	s_waitcnt lgkmcnt(2)
	v_mfma_f32_32x32x16_bf16 v[16:31], v[52:55], v[48:51], v[16:31]
	v_cmp_ge_u32_e32 vcc, v176, v163
	s_waitcnt lgkmcnt(0)
	v_mfma_f32_32x32x16_bf16 v[32:47], v[56:59], v[48:51], v[32:47]
	ds_read_b64_tr_b16 v[52:53], v14 offset:19456
	ds_read_b64_tr_b16 v[54:55], v0 offset:20992
	ds_read_b64_tr_b16 v[56:57], v0 offset:19520
	ds_read_b64_tr_b16 v[58:59], v0 offset:21056
	v_cvt_pk_bf16_f32 v48, v63, v100
	v_cvt_pk_bf16_f32 v49, v101, v102
	v_cvt_pk_bf16_f32 v50, v103, v60
	v_cvt_pk_bf16_f32 v51, v61, v62
	s_waitcnt lgkmcnt(2)
	s_nop 0
	v_mfma_f32_32x32x16_bf16 v[16:31], v[52:55], v[48:51], v[16:31]
	s_waitcnt lgkmcnt(0)
	v_mfma_f32_32x32x16_bf16 v[32:47], v[56:59], v[48:51], v[32:47]
	s_waitcnt vmcnt(8) lgkmcnt(0)
	v_mfma_f32_32x32x16_bf16 v[48:63], v[92:95], v[236:239], 0
	s_waitcnt lgkmcnt(0)
	v_mfma_f32_32x32x16_bf16 v[48:63], v[88:91], v[240:243], v[48:63]
	s_waitcnt lgkmcnt(0)
	v_mfma_f32_32x32x16_bf16 v[48:63], v[84:87], v[244:247], v[48:63]
	s_waitcnt lgkmcnt(0)
	v_mfma_f32_32x32x16_bf16 v[48:63], v[80:83], v[248:251], v[48:63]
	v_min_i32_e32 v80, s44, v169
	v_add_u32_e32 v80, v80, v165
	v_lshl_add_u32 v80, v80, 6, v172
	v_med3_i32 v80, v80, 0, v228
	v_or_b32_e32 v80, v138, v80
	v_mad_u64_u32 v[80:81], s[38:39], v80, s90, v[142:143]
	v_mad_i32_i24 v81, v139, s90, v81
	global_load_dwordx4 v[92:95], v[80:81], off offset:1024
	global_load_dwordx4 v[88:91], v[80:81], off offset:1056
	global_load_dwordx4 v[84:87], v[80:81], off offset:1088
	s_nop 0
	global_load_dwordx4 v[80:83], v[80:81], off offset:1120
	s_waitcnt vmcnt(7)
	ds_write_b128 v175, v[2:5] offset:16384
	s_waitcnt vmcnt(6)
	ds_write_b128 v175, v[6:9] offset:17920
	s_waitcnt vmcnt(5)
	ds_write_b128 v175, v[10:13] offset:19456
	s_waitcnt vmcnt(4)
	ds_write_b128 v175, v[96:99] offset:20992
	v_or_b32_e32 v4, v15, v123
	v_med3_i32 v2, v4, 0, v228
	v_or_b32_e32 v2, v138, v2
	v_mad_u64_u32 v[2:3], s[38:39], v2, s90, v[140:141]
	v_mad_i32_i24 v3, v139, s90, v3
	global_load_dwordx4 v[96:99], v[2:3], off offset:2048
	v_add_u32_e32 v2, 8, v4
	v_med3_i32 v2, v2, 0, v228
	v_or_b32_e32 v2, v138, v2
	v_mad_u64_u32 v[2:3], s[38:39], v2, s90, v[140:141]
	v_mad_i32_i24 v3, v139, s90, v3
	global_load_dwordx4 v[100:103], v[2:3], off offset:2048
	v_add_u32_e32 v2, 16, v4
	v_med3_i32 v2, v2, 0, v228
	v_or_b32_e32 v2, v138, v2
	v_mad_u64_u32 v[2:3], s[38:39], v2, s90, v[140:141]
	v_mad_i32_i24 v3, v139, s90, v3
	global_load_dwordx4 v[104:107], v[2:3], off offset:2048
	v_add_u32_e32 v2, 24, v4
	v_med3_i32 v2, v2, 0, v228
	v_or_b32_e32 v2, v138, v2
	v_mad_u64_u32 v[2:3], s[38:39], v2, s90, v[140:141]
	v_mad_i32_i24 v3, v139, s90, v3
	global_load_dwordx4 v[108:111], v[2:3], off offset:2048
	ds_read2_b32 v[4:5], v173 offset0:31 offset1:32
	ds_read2_b32 v[6:7], v173 offset0:33 offset1:34
	ds_read2_b32 v[12:13], v173 offset0:47 offset1:48
	v_cmp_lt_u32_e64 s[38:39], v176, v137
	s_and_b64 vcc, vcc, s[38:39]
	v_cndmask_b32_e32 v175, v230, v171, vcc
	v_cmp_gt_u32_e32 vcc, 16, v175
	s_waitcnt lgkmcnt(2)
; #define LAS __attribute__((address_space(3)))
; DI float fexp2(float x) { return __builtin_amdgcn_exp2f(x); }
; DI float shx(float v, int o) { int l = (int)__builtin_amdgcn_mbcnt_hi(~0u, __builtin_amdgcn_mbcnt_lo(~0u, 0u)); asm volatile("" : "+v"(l)); return __int_as_float(__builtin_amdgcn_ds_bpermute((l ^ o) << 2, __float_as_int(v))); }
; template <class MaskF>
; DI void attn_rest(const f32x16& S, LAS unsigned char* LV, int lane, f32x16& O0, f32x16& O1, float& m_run, float& l_run, const MaskF& maskf) {
;     const int h = lane >> 5;
;     float sv[16]; float mx = -1e30f;
; #pragma unroll
;     for (int r = 0; r < 16; ++r) { sv[r] = maskf((r & 3) + 8 * (r >> 2), S[r]); mx = fmaxf(mx, sv[r]); }
;     mx = fmaxf(mx, shx(mx, 32));
;     if (__builtin_amdgcn_ballot_w64(mx > m_run) != 0ull) {
;         const float mn = fmaxf(m_run, mx);
;         const float alpha = fexp2(m_run - mn);
;         m_run = mn; l_run *= alpha;
; #pragma unroll
;         for (int i = 0; i < 16; ++i) { O0[i] *= alpha; O1[i] *= alpha; }
;     }
	v_add_f32_e32 v2, v48, v4
	v_add_u32_e32 v4, 2, v175
	v_cndmask_b32_e32 v3, v229, v2, vcc
	v_add_u32_e32 v2, 1, v175
	v_cmp_gt_u32_e32 vcc, 16, v2
	v_add_f32_e32 v2, v49, v5
	ds_read2_b32 v[48:49], v173 offset0:49 offset1:50
	v_cndmask_b32_e32 v2, v229, v2, vcc
	v_cmp_gt_u32_e32 vcc, 16, v4
	s_waitcnt lgkmcnt(2)
	v_add_f32_e32 v4, v50, v6
	v_max3_f32 v8, v3, s83, v2
	v_cndmask_b32_e32 v5, v229, v4, vcc
	v_add_u32_e32 v4, 3, v175
	v_cmp_gt_u32_e32 vcc, 16, v4
	v_add_f32_e32 v4, v51, v7
	v_add_u32_e32 v6, 8, v175
	v_cndmask_b32_e32 v4, v229, v4, vcc
	v_max3_f32 v10, v8, v5, v4
	ds_read2_b32 v[8:9], v173 offset0:39 offset1:40
	v_cmp_gt_u32_e32 vcc, 16, v6
	v_add_u32_e32 v11, 10, v175
	s_waitcnt lgkmcnt(0)
	v_add_f32_e32 v6, v52, v8
	v_cndmask_b32_e32 v7, v229, v6, vcc
	v_add_u32_e32 v6, 9, v175
	v_cmp_gt_u32_e32 vcc, 16, v6
	v_add_f32_e32 v6, v53, v9
	ds_read2_b32 v[8:9], v173 offset0:41 offset1:42
	v_cndmask_b32_e32 v6, v229, v6, vcc
	v_cmp_gt_u32_e32 vcc, 16, v11
	v_add_u32_e32 v11, 11, v175
	v_max3_f32 v10, v10, v7, v6
	s_waitcnt lgkmcnt(0)
	v_add_f32_e32 v8, v54, v8
	v_cndmask_b32_e32 v8, v229, v8, vcc
	v_cmp_gt_u32_e32 vcc, 16, v11
	v_add_f32_e32 v9, v55, v9
	s_nop 0
	v_cndmask_b32_e32 v9, v229, v9, vcc
	v_max3_f32 v15, v10, v8, v9
	v_cmp_lt_u32_e32 vcc, s54, v175
	v_add_f32_e32 v10, v56, v12
	v_add_u32_e32 v12, 18, v175
	v_cndmask_b32_e32 v11, v229, v10, vcc
	v_add_u32_e32 v10, 17, v175
	v_cmp_gt_u32_e32 vcc, 16, v10
	v_add_f32_e32 v10, v57, v13
	s_nop 0
	v_cndmask_b32_e32 v10, v229, v10, vcc
	v_cmp_gt_u32_e32 vcc, 16, v12
	v_add_f32_e32 v12, v58, v48
	v_max3_f32 v15, v15, v11, v10
	v_cndmask_b32_e32 v13, v229, v12, vcc
	v_add_u32_e32 v12, 19, v175
	v_cmp_gt_u32_e32 vcc, 16, v12
	v_add_f32_e32 v12, v59, v49
	ds_read2_b32 v[48:49], v173 offset0:55 offset1:56
	v_cndmask_b32_e32 v12, v229, v12, vcc
	v_max3_f32 v50, v15, v13, v12
	v_add_u32_e32 v15, 24, v175
	v_cmp_gt_u32_e32 vcc, 16, v15
	s_waitcnt lgkmcnt(0)
	v_add_f32_e32 v15, v60, v48
	v_add_u32_e32 v48, 25, v175
	v_cndmask_b32_e32 v15, v229, v15, vcc
	v_cmp_gt_u32_e32 vcc, 16, v48
	v_add_f32_e32 v48, v61, v49
	v_add_u32_e32 v49, 26, v175
	v_cndmask_b32_e32 v48, v229, v48, vcc
	v_max3_f32 v52, v50, v15, v48
	ds_read2_b32 v[50:51], v173 offset0:57 offset1:58
	v_cmp_gt_u32_e32 vcc, 16, v49
	s_waitcnt lgkmcnt(0)
	v_add_f32_e32 v49, v62, v50
	v_add_u32_e32 v50, 27, v175
	v_cndmask_b32_e32 v49, v229, v49, vcc
	v_cmp_gt_u32_e32 vcc, 16, v50
	v_add_f32_e32 v50, v63, v51
	s_nop 0
	v_cndmask_b32_e32 v50, v229, v50, vcc
	v_max3_f32 v51, v52, v49, v50
	v_mov_b32_e32 v52, v205
	s_nop 0
	v_lshlrev_b32_e32 v52, 2, v52
	v_xor_b32_e32 v52, 0x80, v52
	ds_bpermute_b32 v52, v52, v51
	s_waitcnt lgkmcnt(0)
	v_max_f32_e32 v52, v52, v52
	v_max_f32_e32 v51, v51, v52
	v_cmp_gt_f32_e32 vcc, v51, v133
	s_cbranch_vccz .LBB0_346
	v_max_f32_e32 v51, v51, v51
	v_max_f32_e32 v52, v133, v133
	v_max_f32_e32 v51, v52, v51
	v_sub_f32_e32 v52, v133, v51
	v_exp_f32_e32 v52, v52
	v_mov_b32_e32 v133, v51
	v_mul_f32_e32 v159, v159, v52
	v_pk_mul_f32 v[30:31], v[30:31], v[52:53] op_sel_hi:[1,0]
	v_pk_mul_f32 v[28:29], v[28:29], v[52:53] op_sel_hi:[1,0]
	v_pk_mul_f32 v[26:27], v[26:27], v[52:53] op_sel_hi:[1,0]
	v_pk_mul_f32 v[24:25], v[24:25], v[52:53] op_sel_hi:[1,0]
	v_pk_mul_f32 v[22:23], v[22:23], v[52:53] op_sel_hi:[1,0]
	v_pk_mul_f32 v[20:21], v[20:21], v[52:53] op_sel_hi:[1,0]
	v_pk_mul_f32 v[18:19], v[18:19], v[52:53] op_sel_hi:[1,0]
	v_pk_mul_f32 v[16:17], v[16:17], v[52:53] op_sel_hi:[1,0]
	v_pk_mul_f32 v[46:47], v[46:47], v[52:53] op_sel_hi:[1,0]
	v_pk_mul_f32 v[44:45], v[44:45], v[52:53] op_sel_hi:[1,0]
	v_pk_mul_f32 v[42:43], v[42:43], v[52:53] op_sel_hi:[1,0]
	v_pk_mul_f32 v[40:41], v[40:41], v[52:53] op_sel_hi:[1,0]
	v_pk_mul_f32 v[38:39], v[38:39], v[52:53] op_sel_hi:[1,0]
	v_pk_mul_f32 v[36:37], v[36:37], v[52:53] op_sel_hi:[1,0]
	v_pk_mul_f32 v[34:35], v[34:35], v[52:53] op_sel_hi:[1,0]
	v_pk_mul_f32 v[32:33], v[32:33], v[52:53] op_sel_hi:[1,0]
	s_branch .LBB0_346

; #define LAS __attribute__((address_space(3)))
; DI float fexp2(float x) { return __builtin_amdgcn_exp2f(x); }
; DI float shx(float v, int o) { int l = (int)__builtin_amdgcn_mbcnt_hi(~0u, __builtin_amdgcn_mbcnt_lo(~0u, 0u)); asm volatile("" : "+v"(l)); return __int_as_float(__builtin_amdgcn_ds_bpermute((l ^ o) << 2, __float_as_int(v))); }
;     DI void rest(int t, const f32x16& S, LAS unsigned char* LV, int ln, f32x16& O0, f32x16& O1, float& m_run, float& l_run) const { attn_rest(S, LV, ln, O0, O1, m_run, l_run, mask(t)); }
; template <class MaskF>
; DI void attn_rest(const f32x16& S, LAS unsigned char* LV, int lane, f32x16& O0, f32x16& O1, float& m_run, float& l_run, const MaskF& maskf) {
;     const int h = lane >> 5;
;     float sv[16]; float mx = -1e30f;
; #pragma unroll
;     for (int r = 0; r < 16; ++r) { sv[r] = maskf((r & 3) + 8 * (r >> 2), S[r]); mx = fmaxf(mx, sv[r]); }
;     mx = fmaxf(mx, shx(mx, 32));
;     if (__builtin_amdgcn_ballot_w64(mx > m_run) != 0ull) {
;         const float mn = fmaxf(m_run, mx);
;         const float alpha = fexp2(m_run - mn);
;         m_run = mn; l_run *= alpha;
; #pragma unroll
;         for (int i = 0; i < 16; ++i) { O0[i] *= alpha; O1[i] *= alpha; }
;     }
; template <class Desc>
; DI void attn_loop(const Desc& d, int ntiles, const bf16x8 (&qf)[4], LAS unsigned char* LV, int lane, bf16_t* orow) {
;     ...
;     if (ntiles & 1) {
;         const f32x16 Sa = attn_scores(LQ, lane, kA);
;         attn_store_v(LV, lane, vN);
;         d.rest(tl, Sa, LV, lane, O0, O1, m_run, l_run);
.LBB0_352:
	s_or_b64 exec, exec, s[96:97]
	v_and_b32_e32 v0, 1, v167
	v_mov_b32_e32 v135, v139
	v_cmp_eq_u32_e32 vcc, 1, v0
	s_and_saveexec_b64 s[58:59], vcc
	s_cbranch_execz .LBB0_309
	v_cmp_gt_u32_e64 s[38:39], v162, v161
	v_add_u32_e32 v0, 0, v166
	s_waitcnt vmcnt(7) lgkmcnt(0)
	v_mfma_f32_32x32x16_bf16 v[48:63], v[76:79], v[236:239], 0
	s_waitcnt vmcnt(6) lgkmcnt(0)
	v_mfma_f32_32x32x16_bf16 v[48:63], v[72:75], v[240:243], v[48:63]
	s_waitcnt vmcnt(5) lgkmcnt(0)
	v_mfma_f32_32x32x16_bf16 v[48:63], v[68:71], v[244:247], v[48:63]
	s_waitcnt vmcnt(4) lgkmcnt(0)
	v_mfma_f32_32x32x16_bf16 v[48:63], v[64:67], v[248:251], v[48:63]
	v_add_u32_e32 v2, v125, v127
	s_waitcnt vmcnt(3)
	ds_write_b128 v2, v[96:99] offset:16384
	s_waitcnt vmcnt(2)
	ds_write_b128 v2, v[100:103] offset:17920
	s_waitcnt vmcnt(1)
	ds_write_b128 v2, v[104:107] offset:19456
	s_waitcnt vmcnt(0)
	ds_write_b128 v2, v[108:111] offset:20992
	v_add_u32_e32 v2, 4, v161
	v_cmp_ge_i32_e32 vcc, v2, v163
	s_and_b64 vcc, vcc, s[38:39]
	v_sub_u32_e32 v3, v164, v155
	v_cndmask_b32_e32 v64, v230, v3, vcc
	v_sub_u32_e32 v2, v2, v160
	v_sub_u32_e32 v3, v164, v153
	v_lshlrev_b32_e32 v3, 2, v3
	v_mul_i32_i24_e32 v2, 0x7c, v2
	v_add3_u32 v65, v0, v3, v2
	ds_read2_b32 v[2:3], v65 offset0:248 offset1:249
	ds_read2_b32 v[6:7], v65 offset0:250 offset1:251
	v_cmp_gt_u32_e32 vcc, 16, v64
	s_waitcnt lgkmcnt(1)
	v_add_f32_e32 v0, v48, v2
	v_cndmask_b32_e32 v2, v229, v0, vcc
	v_add_u32_e32 v0, 1, v64
	v_cmp_gt_u32_e32 vcc, 16, v0
	v_add_f32_e32 v0, v49, v3
	s_nop 0
	v_cndmask_b32_e32 v4, v229, v0, vcc
	v_add_u32_e32 v0, 2, v64
	v_cmp_gt_u32_e32 vcc, 16, v0
	s_waitcnt lgkmcnt(0)
	v_add_f32_e32 v0, v50, v6
	v_max3_f32 v5, v2, s83, v4
	v_cndmask_b32_e32 v3, v229, v0, vcc
	v_add_u32_e32 v0, 3, v64
	v_cmp_gt_u32_e32 vcc, 16, v0
	v_add_f32_e32 v0, v51, v7
	s_nop 0
	v_cndmask_b32_e32 v0, v229, v0, vcc
	v_max3_f32 v8, v5, v3, v0
	v_add_u32_e32 v5, 0x400, v65
	ds_read2_b32 v[6:7], v5 offset1:1
	v_add_u32_e32 v5, 8, v64
	v_cmp_gt_u32_e32 vcc, 16, v5
	s_waitcnt lgkmcnt(0)
	v_add_f32_e32 v5, v52, v6
	v_cndmask_b32_e32 v6, v229, v5, vcc
	v_add_u32_e32 v5, 9, v64
	v_cmp_gt_u32_e32 vcc, 16, v5
	v_add_f32_e32 v5, v53, v7
	v_add_u32_e32 v7, 0x408, v65
	v_cndmask_b32_e32 v5, v229, v5, vcc
	v_max3_f32 v10, v8, v6, v5
	ds_read2_b32 v[8:9], v7 offset1:1
	v_add_u32_e32 v7, 10, v64
	v_cmp_gt_u32_e32 vcc, 16, v7
	s_waitcnt lgkmcnt(0)
	v_add_f32_e32 v7, v54, v8
	v_add_u32_e32 v8, 11, v64
	v_cndmask_b32_e32 v7, v229, v7, vcc
	v_cmp_gt_u32_e32 vcc, 16, v8
	v_add_f32_e32 v8, v55, v9
	v_add_u32_e32 v9, 0x420, v65
	v_cndmask_b32_e32 v8, v229, v8, vcc
	v_max3_f32 v12, v10, v7, v8
	ds_read2_b32 v[10:11], v9 offset1:1
	v_cmp_lt_u32_e32 vcc, s54, v64
	s_waitcnt lgkmcnt(0)
	v_add_f32_e32 v9, v56, v10
	v_cndmask_b32_e32 v10, v229, v9, vcc
	v_add_u32_e32 v9, 17, v64
	v_cmp_gt_u32_e32 vcc, 16, v9
	v_add_f32_e32 v9, v57, v11
	v_add_u32_e32 v11, 0x428, v65
	v_cndmask_b32_e32 v9, v229, v9, vcc
	v_max3_f32 v14, v12, v10, v9
	ds_read2_b32 v[12:13], v11 offset1:1
	v_add_u32_e32 v11, 18, v64
	v_cmp_gt_u32_e32 vcc, 16, v11
	s_waitcnt lgkmcnt(0)
	v_add_f32_e32 v11, v58, v12
	v_cndmask_b32_e32 v12, v229, v11, vcc
	v_add_u32_e32 v11, 19, v64
	v_cmp_gt_u32_e32 vcc, 16, v11
	v_add_f32_e32 v11, v59, v13
	v_add_u32_e32 v13, 0x440, v65
	v_cndmask_b32_e32 v11, v229, v11, vcc
	v_max3_f32 v48, v14, v12, v11
	ds_read2_b32 v[14:15], v13 offset1:1
	v_add_u32_e32 v13, 24, v64
	v_cmp_gt_u32_e32 vcc, 16, v13
	s_waitcnt lgkmcnt(0)
	v_add_f32_e32 v13, v60, v14
	v_add_u32_e32 v14, 25, v64
	v_cndmask_b32_e32 v13, v229, v13, vcc
	v_cmp_gt_u32_e32 vcc, 16, v14
	v_add_f32_e32 v14, v61, v15
	v_add_u32_e32 v15, 0x448, v65
	v_cndmask_b32_e32 v14, v229, v14, vcc
	v_max3_f32 v50, v48, v13, v14
	ds_read2_b32 v[48:49], v15 offset1:1
	v_add_u32_e32 v15, 26, v64
	v_cmp_gt_u32_e32 vcc, 16, v15
	s_waitcnt lgkmcnt(0)
	v_add_f32_e32 v15, v62, v48
	v_add_u32_e32 v48, 27, v64
	v_cndmask_b32_e32 v15, v229, v15, vcc
	v_cmp_gt_u32_e32 vcc, 16, v48
	v_add_f32_e32 v48, v63, v49
	s_nop 0
	v_cndmask_b32_e32 v48, v229, v48, vcc
	v_max3_f32 v49, v50, v15, v48
	v_mov_b32_e32 v50, v205
	s_nop 0
	v_lshlrev_b32_e32 v50, 2, v50
	v_xor_b32_e32 v50, 0x80, v50
	ds_bpermute_b32 v50, v50, v49
	s_waitcnt lgkmcnt(0)
	v_max_f32_e32 v50, v50, v50
	v_max_f32_e32 v49, v49, v50
	v_cmp_gt_f32_e32 vcc, v49, v133
	s_cbranch_vccz .LBB0_308
	v_max_f32_e32 v49, v49, v49
	v_max_f32_e32 v50, v133, v133
	v_max_f32_e32 v49, v50, v49
	v_sub_f32_e32 v50, v133, v49
	v_exp_f32_e32 v50, v50
	v_mov_b32_e32 v133, v49
	v_mul_f32_e32 v159, v159, v50
	v_pk_mul_f32 v[30:31], v[30:31], v[50:51] op_sel_hi:[1,0]
	v_pk_mul_f32 v[28:29], v[28:29], v[50:51] op_sel_hi:[1,0]
	v_pk_mul_f32 v[26:27], v[26:27], v[50:51] op_sel_hi:[1,0]
	v_pk_mul_f32 v[24:25], v[24:25], v[50:51] op_sel_hi:[1,0]
	v_pk_mul_f32 v[22:23], v[22:23], v[50:51] op_sel_hi:[1,0]
	v_pk_mul_f32 v[20:21], v[20:21], v[50:51] op_sel_hi:[1,0]
	v_pk_mul_f32 v[18:19], v[18:19], v[50:51] op_sel_hi:[1,0]
	v_pk_mul_f32 v[16:17], v[16:17], v[50:51] op_sel_hi:[1,0]
	v_pk_mul_f32 v[46:47], v[46:47], v[50:51] op_sel_hi:[1,0]
	v_pk_mul_f32 v[44:45], v[44:45], v[50:51] op_sel_hi:[1,0]
	v_pk_mul_f32 v[42:43], v[42:43], v[50:51] op_sel_hi:[1,0]
	v_pk_mul_f32 v[40:41], v[40:41], v[50:51] op_sel_hi:[1,0]
	v_pk_mul_f32 v[38:39], v[38:39], v[50:51] op_sel_hi:[1,0]
	v_pk_mul_f32 v[36:37], v[36:37], v[50:51] op_sel_hi:[1,0]
	v_pk_mul_f32 v[34:35], v[34:35], v[50:51] op_sel_hi:[1,0]
	v_pk_mul_f32 v[32:33], v[32:33], v[50:51] op_sel_hi:[1,0]
	s_branch .LBB0_308

; DI void ret_phase(LAS unsigned char* L, const bf16_t* P, bf16_t* R, const float* lg2tab, int nseq) {
;     ...
;             bf16x8 qa[2][8];
; #pragma unroll
;             for (int s = 0; s < 8; ++s) {
;                 const int ko = (32 * s + 8 * quad) * 2;
;                 qa[0][s] = lds_r128(L, RT_OQ + ((2 * wh) * 16 + l15) * RT_RSQ + ko); qa[1][s] = lds_r128(L, RT_OQ + ((2 * wh + 1) * 16 + l15) * RT_RSQ + ko);
;             }
;             f32x4 s0 = (f32x4){0.f, 0.f, 0.f, 0.f}, s1 = s0;
; #pragma unroll
;             for (int hs = 0; hs < 2; ++hs) {
;                 bf16x8 xa[4];
; #pragma unroll
;                 for (int s = 0; s < 4; ++s) xa[s] = lds_r128(L, RT_OK + (xb * 16 + l15) * RT_RSQ + (32 * (4 * hs + s) + 8 * quad) * 2);
; #pragma unroll
;                 for (int s = 0; s < 4; ++s) { s0 = mfma16(xa[s], qa[0][4 * hs + s], s0); s1 = mfma16(xa[s], qa[1][4 * hs + s], s1); }
;             }
; #pragma unroll
;             for (int t = 0; t < 2; ++t) {
;                 const f32x4 sx = t ? s1 : s0;
;                 const int q = (2 * wh + t) * 16 + l15, key0 = xb * 16 + 4 * quad;
;                 u32x2 w; w.x = pack_bf16(sx[0] * dm[t][0], sx[1] * dm[t][1]); w.y = pack_bf16(sx[2] * dm[t][2], sx[3] * dm[t][3]);
;                 *(LAS u32x2*)(L + RT_OP + q * RT_RSV + key0 * 2) = w;
;             }
;             f32x4 o0 = (f32x4){0.f, 0.f, 0.f, 0.f}, o1 = o0;
; #pragma unroll
;             for (int hs = 0; hs < 2; ++hs) {
;                 bf16x8 xa[4];
; #pragma unroll
;                 for (int s = 0; s < 4; ++s) xa[s] = lds_r128(L, RT_OS + (xb * 16 + l15) * RT_RSQ + (32 * (4 * hs + s) + 8 * quad) * 2);
; #pragma unroll
;                 for (int s = 0; s < 4; ++s) { o0 = mfma16(qa[0][4 * hs + s], xa[s], o0); o1 = mfma16(qa[1][4 * hs + s], xa[s], o1); }
;             }
; #pragma unroll
;             for (int r = 0; r < 4; ++r) { o0[r] *= qd[0][r]; o1[r] *= qd[1][r]; }
; #pragma unroll
;             for (int j = 0; j < 8; ++j) st[j] *= sd;
; #pragma unroll
;             for (int s = 0; s < 2; ++s) {
;                 const int kr = 32 * s + 8 * quad + q4;
;                 const bf16x8 bv = cat4(lds_tr(L, RT_OVK + kr * RT_RSV + (xb * 16 + 4 * p4) * 2), lds_tr(L, RT_OVK + (kr + 4) * RT_RSV + (xb * 16 + 4 * p4) * 2));
; #pragma unroll
;                 for (int hj = 0; hj < 2; ++hj) {
;                     bf16x8 ak[4];
; #pragma unroll
.LBB0_898:
	v_and_b32_e32 v185, 15, v191
	v_or_b32_e32 v70, s34, v185
	v_and_b32_e32 v186, -16, v191
	v_mul_u32_u24_e32 v184, 0x210, v70
	v_add3_u32 v145, 0, v184, v186
	ds_read_b128 v[70:73], v145 offset:33792
	v_or_b32_e32 v189, s31, v185
	v_mul_lo_u32 v74, v189, s79
	v_add3_u32 v187, 0, v74, v186
	ds_read_b128 v[106:109], v187
	ds_read_b128 v[110:113], v187 offset:8448
	ds_read_b128 v[78:81], v145 offset:33856
	ds_read_b128 v[114:117], v187 offset:64
	ds_read_b128 v[196:199], v187 offset:8512
	ds_read_b128 v[82:85], v145 offset:33920
	s_waitcnt lgkmcnt(5)
	v_mfma_f32_16x16x32_bf16 v[74:77], v[70:73], v[106:109], 0
	ds_read_b128 v[200:203], v187 offset:128
	ds_read_b128 v[206:209], v187 offset:8576
	v_ashrrev_i32_e32 v188, 4, v191
	v_pk_mul_f32 v[42:43], v[150:151], v[42:43]
	s_waitcnt lgkmcnt(6)
	v_mfma_f32_16x16x32_bf16 v[70:73], v[70:73], v[110:113], 0
	s_xor_b64 s[40:41], s[24:25], -1
	s_add_i32 s25, s26, -1
	s_and_b32 s24, s25, 1
	s_waitcnt lgkmcnt(4)
	v_mfma_f32_16x16x32_bf16 v[74:77], v[78:81], v[114:117], v[74:77]
	s_andn2_b64 vcc, exec, s[40:41]
	s_waitcnt lgkmcnt(3)
	v_mfma_f32_16x16x32_bf16 v[70:73], v[78:81], v[196:199], v[70:73]
	ds_read_b128 v[78:81], v145 offset:33984
	ds_read_b128 v[118:121], v187 offset:192
	ds_read_b128 v[102:105], v187 offset:8640
	ds_read_b128 v[90:93], v145 offset:34048
	s_waitcnt lgkmcnt(5)
	v_mfma_f32_16x16x32_bf16 v[74:77], v[82:85], v[200:203], v[74:77]
	s_waitcnt lgkmcnt(4)
	v_mfma_f32_16x16x32_bf16 v[70:73], v[82:85], v[206:209], v[70:73]
	ds_read_b128 v[98:101], v187 offset:256
	ds_read_b128 v[82:85], v187 offset:8704
	ds_read_b128 v[210:213], v145 offset:34112
	ds_read_b128 v[86:89], v187 offset:320
	s_waitcnt lgkmcnt(6)
	v_mfma_f32_16x16x32_bf16 v[74:77], v[78:81], v[118:121], v[74:77]
	s_waitcnt lgkmcnt(5)
	v_mfma_f32_16x16x32_bf16 v[70:73], v[78:81], v[102:105], v[70:73]
	s_waitcnt lgkmcnt(3)
	v_mfma_f32_16x16x32_bf16 v[74:77], v[90:93], v[98:101], v[74:77]
	s_waitcnt lgkmcnt(2)
	v_mfma_f32_16x16x32_bf16 v[214:217], v[90:93], v[82:85], v[70:73]
	ds_read_b128 v[218:221], v145 offset:34176
	s_nop 2
	ds_read_b128 v[70:73], v187 offset:384
	ds_read_b128 v[222:225], v145 offset:34240
	ds_read_b128 v[94:97], v187 offset:8768
	ds_read_b128 v[78:81], v187 offset:448
	v_add_u32_e32 v145, 0x10800, v145
	s_waitcnt lgkmcnt(5)
	v_mfma_f32_16x16x32_bf16 v[74:77], v[210:213], v[86:89], v[74:77]
	s_waitcnt lgkmcnt(3)
	v_mfma_f32_16x16x32_bf16 v[236:239], v[218:221], v[70:73], v[74:77]
	ds_read_b128 v[90:93], v187 offset:8832
	s_nop 4
	ds_read_b128 v[74:77], v187 offset:8896
	v_lshlrev_b32_e32 v187, 3, v188
	s_waitcnt lgkmcnt(3)
	v_mfma_f32_16x16x32_bf16 v[210:213], v[210:213], v[94:97], v[214:217]
	s_waitcnt lgkmcnt(2)
	v_mfma_f32_16x16x32_bf16 v[236:239], v[222:225], v[78:81], v[236:239]
	s_waitcnt lgkmcnt(1)
	v_mfma_f32_16x16x32_bf16 v[210:213], v[218:221], v[90:93], v[210:213]
	s_waitcnt lgkmcnt(0)
	v_mfma_f32_16x16x32_bf16 v[210:213], v[222:225], v[74:77], v[210:213]
	s_nop 3
	v_mul_f32_e32 v190, v172, v236
	v_mul_f32_e32 v192, v173, v237
	v_cvt_pk_bf16_f32 v192, v190, v192
	v_mul_f32_e32 v190, v174, v238
	v_mul_f32_e32 v193, v175, v239
	v_cvt_pk_bf16_f32 v193, v190, v193
	v_mul_lo_u32 v190, v189, s91
	v_add3_u32 v189, s36, v187, v190
	ds_write_b64 v189, v[192:193]
	v_mul_f32_e32 v192, v176, v210
	v_mul_f32_e32 v193, v177, v211
	v_cvt_pk_bf16_f32 v192, v192, v193
	v_mul_f32_e32 v193, v178, v212
	v_mul_f32_e32 v204, v179, v213
	v_cvt_pk_bf16_f32 v193, v193, v204
	ds_write_b64 v189, v[192:193] offset:2304
	ds_read_b128 v[210:213], v145
	ds_read_b128 v[214:217], v145 offset:64
	s_waitcnt lgkmcnt(1)
	v_mfma_f32_16x16x32_bf16 v[106:109], v[106:109], v[210:213], 0
	v_bfe_u32 v189, v191, 2, 2
	v_mfma_f32_16x16x32_bf16 v[110:113], v[110:113], v[210:213], 0
	ds_read_b128 v[210:213], v145 offset:128
	ds_read_b128 v[218:221], v145 offset:192
	s_waitcnt lgkmcnt(2)
	v_mfma_f32_16x16x32_bf16 v[222:225], v[114:117], v[214:217], v[106:109]
	ds_read_b128 v[236:239], v145 offset:256
	ds_read_b128 v[240:243], v145 offset:320
	ds_read_b128 v[114:117], v145 offset:384
	v_pk_mul_f32 v[106:107], v[150:151], v[38:39]
	v_mfma_f32_16x16x32_bf16 v[196:199], v[196:199], v[214:217], v[110:113]
	v_mul_f32_e64 v214, v150, v62
	v_mul_f32_e64 v215, v151, v63
	v_pk_mul_f32 v[62:63], v[150:151], v[50:51]
	v_pk_mul_f32 v[50:51], v[150:151], v[66:67]
	s_waitcnt lgkmcnt(4)
	v_mfma_f32_16x16x32_bf16 v[200:203], v[200:203], v[210:213], v[222:225]
	ds_read_b128 v[110:113], v145 offset:448
	v_mov_b32_e32 v145, v144
	v_pk_mul_f32 v[108:109], v[144:145], v[40:41]
	v_mfma_f32_16x16x32_bf16 v[38:41], v[206:209], v[210:213], v[196:199]
	v_mul_f32_e64 v216, v144, v64
	v_mul_f32_e64 v217, v145, v65
	v_pk_mul_f32 v[64:65], v[144:145], v[52:53]
	v_pk_mul_f32 v[52:53], v[144:145], v[68:69]
	s_waitcnt lgkmcnt(4)
	v_mfma_f32_16x16x32_bf16 v[118:121], v[118:121], v[218:221], v[200:203]
	v_mul_f32_e64 v198, v144, v56
	v_mul_f32_e64 v199, v145, v57
	v_pk_mul_f32 v[196:197], v[150:151], v[54:55]
	v_pk_mul_f32 v[56:57], v[144:145], v[60:61]
	v_pk_mul_f32 v[54:55], v[150:151], v[58:59]
	v_mfma_f32_16x16x32_bf16 v[58:61], v[102:105], v[218:221], v[38:41]
	v_mul_f32_e64 v44, v144, v44
	v_mul_f32_e64 v45, v145, v45
	s_waitcnt lgkmcnt(3)
	v_mfma_f32_16x16x32_bf16 v[66:69], v[98:101], v[236:239], v[118:121]
	v_or_b32_e32 v100, v187, v189
	v_lshlrev_b32_e32 v244, 1, v189
	v_or_b32_e32 v244, v187, v244
	v_lshlrev_b32_e32 v38, 3, v191
	v_and_b32_e32 v38, 24, v38
	v_mfma_f32_16x16x32_bf16 v[58:61], v[82:85], v[236:239], v[58:61]
	v_mul_lo_u32 v83, v100, s91
	v_or_b32_e32 v82, s35, v38
	v_mul_lo_u32 v101, v244, s91
	s_waitcnt lgkmcnt(2)
; #define LAS __attribute__((address_space(3)))
; DI s16x4 lds_tr(LAS unsigned char* L, int off) { return __builtin_amdgcn_ds_read_tr16_b64_v4i16((LAS s16x4*)(L + off)); }
; DI bf16x8 cat4(s16x4 lo, s16x4 hi) { return __builtin_shufflevector(lo, hi, 0, 1, 2, 3, 4, 5, 6, 7); }
; DI f32x4 mfma16(bf16x8 a, bf16x8 b, f32x4 c) { return __builtin_amdgcn_mfma_f32_16x16x32_bf16(a, b, c, 0, 0, 0); }
; DI bf16x8 pack8(const float* v) { u32x4 w; w.x = pack_bf16(v[0], v[1]); w.y = pack_bf16(v[2], v[3]); w.z = pack_bf16(v[4], v[5]); w.w = pack_bf16(v[6], v[7]); return __builtin_bit_cast(bf16x8, w); }
; DI void ret_stage(LAS unsigned char* L, int tid, int vbuf, float kd, const bf16x8 (&sq)[4], const bf16x8 (&sk)[4], const bf16x8& sv) {
; #pragma unroll
;     for (int i = 0; i < 4; ++i) { const int idx = tid + NTHR * i, row = idx >> 5, ch = idx & 31; lds_w128(L, RT_OQ + row * RT_RSQ + ch * 16, sq[i]); lds_w128(L, RT_OK + row * RT_RSQ + ch * 16, sk[i]); }
;     const int row = tid >> 3, ch = tid & 7;
;     lds_w128(L, RT_OV + vbuf * 64 * RT_RSV + row * RT_RSV + ch * 16, sv);
;     float f[8]; unpack8(__builtin_bit_cast(u32x4, sv), f);
; #pragma unroll
;     for (int e = 0; e < 8; ++e) f[e] *= kd;
;     lds_w128(L, RT_OVK + row * RT_RSV + ch * 16, pack8(f));
; }
; DI void ret_phase(LAS unsigned char* L, const bf16_t* P, bf16_t* R, const float* lg2tab, int nseq) {
;     ...
; #pragma unroll
;             for (int s = 0; s < 2; ++s) {
;                 const int kr = 32 * s + 8 * quad + q4;
;                 const bf16x8 bv = cat4(lds_tr(L, RT_OVK + kr * RT_RSV + (xb * 16 + 4 * p4) * 2), lds_tr(L, RT_OVK + (kr + 4) * RT_RSV + (xb * 16 + 4 * p4) * 2));
; #pragma unroll
;                 for (int hj = 0; hj < 2; ++hj) {
;                     bf16x8 ak[4];
; #pragma unroll
;                     for (int j = 0; j < 4; ++j) { const int db = 8 * wh + 4 * hj + j; ak[j] = cat4(lds_tr(L, RT_OK + kr * RT_RSQ + (db * 16 + 4 * p4) * 2), lds_tr(L, RT_OK + (kr + 4) * RT_RSQ + (db * 16 + 4 * p4) * 2)); }
; #pragma unroll
;                     for (int j = 0; j < 4; ++j) st[4 * hj + j] = mfma16(ak[j], bv, st[4 * hj + j]);
;                 }
;             }
;             __syncthreads();
;             if (step + 1 < 64) ret_stage(L, tid, cur ^ 1, kdv, sq, sk, sv);
	v_mfma_f32_16x16x32_bf16 v[66:69], v[86:89], v[240:243], v[66:69]
	v_add3_u32 v39, v101, v82, s77
	ds_read_b64_tr_b16 v[84:85], v39
	v_or_b32_e32 v39, 1, v244
	v_mfma_f32_16x16x32_bf16 v[58:61], v[94:97], v[240:243], v[58:61]
	v_mul_f32_e64 v40, v144, v48
	v_mul_f32_e64 v41, v145, v49
	v_add_u32_e32 v48, 0x90, v101
	v_mul_lo_u32 v39, v39, s72
	s_waitcnt lgkmcnt(2)
	v_mfma_f32_16x16x32_bf16 v[66:69], v[70:73], v[114:117], v[66:69]
	v_or_b32_e32 v102, s37, v38
	v_mul_lo_u32 v86, v244, s79
	v_add3_u32 v104, v48, v39, v102
	v_add3_u32 v103, 0, v86, v102
	v_mfma_f32_16x16x32_bf16 v[58:61], v[90:93], v[114:117], v[58:61]
	ds_read_b64_tr_b16 v[90:91], v104 offset:33792
	ds_read_b64_tr_b16 v[88:89], v103 offset:33792
	v_add3_u32 v49, v48, v82, s77
	v_pk_mul_f32 v[38:39], v[150:151], v[46:47]
	s_waitcnt lgkmcnt(3)
	v_mfma_f32_16x16x32_bf16 v[70:73], v[78:81], v[110:113], v[66:69]
	ds_read_b64_tr_b16 v[86:87], v49
	s_nop 1
	ds_read_b64_tr_b16 v[68:69], v104 offset:33824
	ds_read_b64_tr_b16 v[66:67], v103 offset:33824
	ds_read_b64_tr_b16 v[46:47], v103 offset:33856
	ds_read_b64_tr_b16 v[48:49], v104 offset:33856
	ds_read_b64_tr_b16 v[78:79], v103 offset:33888
	ds_read_b64_tr_b16 v[80:81], v104 offset:33888
	v_mfma_f32_16x16x32_bf16 v[74:77], v[74:77], v[110:113], v[58:61]
	s_waitcnt lgkmcnt(6)
	v_mfma_f32_16x16x32_bf16 v[58:61], v[88:91], v[84:87], v[106:109]
	ds_read_b64_tr_b16 v[88:89], v103 offset:33920
	ds_read_b64_tr_b16 v[90:91], v104 offset:33920
	ds_read_b64_tr_b16 v[92:93], v103 offset:33952
	ds_read_b64_tr_b16 v[94:95], v104 offset:33952
	ds_read_b64_tr_b16 v[96:97], v103 offset:33984
	s_waitcnt lgkmcnt(5)
	v_mfma_f32_16x16x32_bf16 v[78:81], v[78:81], v[84:87], v[62:65]
	ds_read_b64_tr_b16 v[98:99], v104 offset:33984
	s_nop 1
	ds_read_b64_tr_b16 v[62:63], v103 offset:34016
	ds_read_b64_tr_b16 v[64:65], v104 offset:34016
	s_waitcnt lgkmcnt(6)
	v_mfma_f32_16x16x32_bf16 v[88:91], v[88:91], v[84:87], v[54:57]
	s_nop 2
	v_mul_lo_u32 v56, v244, s72
	s_waitcnt lgkmcnt(4)
	v_mfma_f32_16x16x32_bf16 v[92:95], v[92:95], v[84:87], v[50:53]
	v_add_u32_e32 v54, 0x1200, v101
	v_add3_u32 v55, v54, v82, s77
	v_add3_u32 v104, v56, v54, v102
	v_add_u32_e32 v50, 0x1290, v101
	v_add3_u32 v105, v56, v50, v102
	s_waitcnt lgkmcnt(2)
	v_mfma_f32_16x16x32_bf16 v[96:99], v[96:99], v[84:87], v[38:41]
	s_nop 2
	ds_read_b64_tr_b16 v[40:41], v105 offset:46464
	ds_read_b64_tr_b16 v[38:39], v104 offset:46080
	ds_read_b64_tr_b16 v[100:101], v55
	v_add3_u32 v50, v50, v82, s77
	ds_read_b64_tr_b16 v[102:103], v50
	ds_read_b64_tr_b16 v[52:53], v105 offset:46496
	ds_read_b64_tr_b16 v[50:51], v104 offset:46112
	ds_read_b64_tr_b16 v[54:55], v104 offset:46144
	v_mfma_f32_16x16x32_bf16 v[66:69], v[66:69], v[84:87], v[214:217]
	s_waitcnt lgkmcnt(3)
	v_mfma_f32_16x16x32_bf16 v[38:41], v[38:41], v[100:103], v[58:61]
	ds_read_b64_tr_b16 v[56:57], v105 offset:46528
	s_nop 1
	ds_read_b64_tr_b16 v[58:59], v104 offset:46176
	v_mfma_f32_16x16x32_bf16 v[46:49], v[46:49], v[84:87], v[196:199]
	v_mfma_f32_16x16x32_bf16 v[42:45], v[62:65], v[84:87], v[42:45]
	s_waitcnt lgkmcnt(3)
	v_mfma_f32_16x16x32_bf16 v[62:65], v[50:53], v[100:103], v[66:69]
	ds_read_b64_tr_b16 v[60:61], v105 offset:46560
	s_nop 1
	ds_read_b64_tr_b16 v[66:67], v104 offset:46208
	s_waitcnt lgkmcnt(3)
	v_mfma_f32_16x16x32_bf16 v[54:57], v[54:57], v[100:103], v[46:49]
	ds_read_b64_tr_b16 v[68:69], v105 offset:46592
	s_nop 1
	ds_read_b64_tr_b16 v[46:47], v104 offset:46240
	ds_read_b64_tr_b16 v[48:49], v105 offset:46624
	s_waitcnt lgkmcnt(4)
	v_mfma_f32_16x16x32_bf16 v[50:53], v[58:61], v[100:103], v[78:81]
	s_nop 2
	ds_read_b64_tr_b16 v[78:79], v104 offset:46272
	ds_read_b64_tr_b16 v[80:81], v105 offset:46656
	ds_read_b64_tr_b16 v[84:85], v104 offset:46304
	ds_read_b64_tr_b16 v[86:87], v105 offset:46688
	s_waitcnt lgkmcnt(0)
	v_mfma_f32_16x16x32_bf16 v[58:61], v[66:69], v[100:103], v[88:91]
	s_barrier
	v_mfma_f32_16x16x32_bf16 v[66:69], v[46:49], v[100:103], v[92:95]
	v_mfma_f32_16x16x32_bf16 v[46:49], v[78:81], v[100:103], v[96:99]
	v_mfma_f32_16x16x32_bf16 v[42:45], v[84:87], v[100:103], v[42:45]
	s_cbranch_vccnz .LBB0_895
	s_xor_b32 s39, s24, 1
	s_mulk_i32 s39, 0x2400
	s_add_i32 s39, s39, 0
	s_add_i32 s39, s39, 0x18c00
	v_add3_u32 v78, s39, v159, v160
	s_waitcnt vmcnt(8)
	ds_write_b128 v180, v[2:5]
	s_waitcnt vmcnt(7)
	ds_write_b128 v167, v[6:9] offset:33792
	s_waitcnt vmcnt(6)
	ds_write_b128 v181, v[10:13]
	s_waitcnt vmcnt(5)
	ds_write_b128 v168, v[14:17] offset:33792
	s_waitcnt vmcnt(4)
	ds_write_b128 v182, v[18:21]
	s_waitcnt vmcnt(3)
	ds_write_b128 v169, v[22:25] offset:33792
	s_waitcnt vmcnt(2)
	ds_write_b128 v183, v[26:29]
	s_waitcnt vmcnt(1)
	ds_write_b128 v170, v[30:33] offset:33792
	s_waitcnt vmcnt(0)
	ds_write_b128 v78, v[34:37]
	v_lshlrev_b32_e32 v78, 16, v34
	v_and_b32_e32 v79, 0xffff0000, v34
	v_lshlrev_b32_e32 v80, 16, v35
	v_and_b32_e32 v81, 0xffff0000, v35
	v_lshlrev_b32_e32 v84, 16, v36
	v_and_b32_e32 v85, 0xffff0000, v36
	v_lshlrev_b32_e32 v86, 16, v37
	v_and_b32_e32 v87, 0xffff0000, v37
	v_pk_mul_f32 v[78:79], v[146:147], v[78:79]
	v_pk_mul_f32 v[80:81], v[146:147], v[80:81]
	v_pk_mul_f32 v[84:85], v[146:147], v[84:85]
	v_pk_mul_f32 v[86:87], v[146:147], v[86:87]
	v_cvt_pk_bf16_f32 v78, v78, v79
	v_cvt_pk_bf16_f32 v79, v80, v81
	v_cvt_pk_bf16_f32 v80, v84, v85
	v_cvt_pk_bf16_f32 v81, v86, v87
	ds_write_b128 v171, v[78:81]
	s_branch .LBB0_895
